# rg output tile: final barrier skipped when the next item is another rg tile; gate loads issued by the two consuming waves only; stale wait-state pads removed from the rg prologues
# speedup vs baseline: 1.0289x; 1.0017x over previous
; __device__ __forceinline__ bf16_t f2bf(float f) { return (bf16_t)(pack2(f, 0.f) & 0xffffu); }
; __device__ __forceinline__ float bf2f(bf16_t h) { return __uint_as_float(((unsigned)h) << 16); }
; __device__ void rg_tile(unsigned char* lds, const Params& p, int l, int b, int ck, int hh, bool outmode) {
;     ...
;   const int chm_ = hh * 64 + (w & 3) * 16 + lr, dm_ = w >> 2;
;   const float br = p.in[22][(size_t)l * 1024 + (dm_ * 2 + 0) * 256 + chm_];
;   const float bi = p.in[22][(size_t)l * 1024 + (dm_ * 2 + 1) * 256 + chm_];
;   const float lam_ = p.in[23][(size_t)l * 512 + dm_ * 256 + chm_];
;   {
;     const int i = tid & 63, tq = tid >> 6;
;     const int ch = hh * 64 + i;
;     const float* wc = p.in[20] + (size_t)l * 4 * 256 + ch;
;     const float w0 = wc[0], w1 = wc[256], w2 = wc[512], w3 = wc[768];
; #pragma unroll
;     for (int ii = 0; ii < 8; ++ii) {
;       const int tt = tq * 8 + ii;
;       const int tp = t0 + tt;
;       const int tm1 = tp - 1 >= 0 ? tp - 1 : 0, tp1 = tp + 1 < L ? tp + 1 : L - 1, tp2 = tp + 2 < L ? tp + 2 : L - 1;
;       const float z0 = bf2f(z[(size_t)(rowbase + tm1) * ZS + 2816 + ch]);
;       const float z1 = bf2f(z[(size_t)(rowbase + tp) * ZS + 2816 + ch]);
;       const float z2 = bf2f(z[(size_t)(rowbase + tp1) * ZS + 2816 + ch]);
;       const float z3 = bf2f(z[(size_t)(rowbase + tp2) * ZS + 2816 + ch]);
;       float xr = w1 * z1;
;       xr += (tp - 1 >= 0 ? w0 : 0.f) * z0;
;       xr += (tp + 1 < L ? w2 : 0.f) * z2;
;       xr += (tp + 2 < L ? w3 : 0.f) * z3;
;       XR[tt * 65 + i] = xr;
;       XB[tt * 72 + i] = f2bf(xr);
;     }
;     const bf16_t* rgw = (const bf16_t*)(p.ws + OFF_RGW);
; #pragma unroll
;     for (int q = 0; q < 4; ++q) {
;       const int id = tid + 512 * q;
;       const int row = id >> 3, kc = id & 7;
;       *(uint4*)(WT + row * 72 + kc * 8) = *(const uint4*)(rgw + ((size_t)((l * 4 + (row >> 6)) * 4 + hh)) * 4096 + (row & 63) * 64 + kc * 8);
; __global__ void __launch_bounds__(512) fwd_kernel(Params p) {
;     ...
;         const int tile = item - 576;
;         const int hh = tile & 3, ck = (tile >> 2) % 36, b = tile / 144;
;         rg_tile(lds, p, l, b, ck, hh, false);
.LBB0_326:
	s_andn2_b64 vcc, exec, s[0:1]
	s_cbranch_vccnz .LBB0_330
	s_add_i32 s0, s20, 0xfffffdc0
	s_lshr_b32 s1, s0, 2
	s_mul_i32 s2, s1, 0xe38f
	s_lshr_b32 s2, s2, 21
	s_mul_i32 s2, s2, 36
	s_sub_i32 s1, s1, s2
	s_mul_i32 s0, s0, 0xe38f
	s_and_b32 s2, s1, 0xffff
	s_lshr_b32 s3, s0, 23
	v_mov_b32_e32 v29, v195
	s_lshl_b32 s0, s2, 6
	s_lshl_b32 s4, s3, 8
	s_and_b32 s5, s20, 3
	s_add_i32 s1, s0, 0xffffff00
	v_ashrrev_i32_e32 v28, 6, v29
	s_add_i32 s6, s4, 0x4000
	s_lshl_b32 s7, s3, 11
	v_and_b32_e32 v6, 15, v29
	s_cmp_lt_u32 s2, 4
	s_movk_i32 s4, 0x800
	v_lshlrev_b32_e32 v0, 4, v28
	v_ashrrev_i32_e32 v35, 8, v29
	s_cselect_b32 s4, 0x100, s4
	s_cselect_b32 s9, s0, s1
	s_cselect_b32 s6, s6, s7
	v_readfirstlane_b32 s44, v195
	s_mov_b32 s47, s4
	s_mov_b32 s48, s6
	s_mov_b32 s49, s9
	s_lshl_b32 s50, s5, 7
	s_lshr_b32 s44, s44, 6
	s_lshl_b32 s45, s44, 3
	s_add_i32 s45, s45, s49
	s_add_i32 s46, s47, -1
	s_addk_i32 s50, 0x1600
	v_and_b32_e32 v185, 63, v195
	v_lshl_add_u32 v180, v185, 1, s50
	v_readlane_b32 s52, v254, 3
	v_readlane_b32 s53, v254, 4
	s_lshl_b32 s51, s5, 8
	v_lshl_add_u32 v181, v185, 2, s51
	s_nop 2
	global_load_dword v165, v181, s[52:53]
	s_nop 1
	global_load_dword v166, v181, s[52:53] offset:1024
	s_nop 0
	global_load_dword v167, v181, s[52:53] offset:2048
	global_load_dword v168, v181, s[52:53] offset:3072
	s_add_i32 s54, s45, s48
	s_mul_i32 s54, s54, 0x1a00
	v_add_u32_e32 v181, s54, v180
	s_add_i32 s55, s45, -1
	s_max_i32 s55, s55, 0
	s_add_i32 s55, s55, s48
	s_mul_i32 s55, s55, 0x1a00
	v_add_u32_e32 v184, s55, v180
	global_load_ushort v154, v184, s[88:89]
	global_load_ushort v155, v181, s[88:89]
	v_add_u32_e32 v181, 0x1a00, v181
	global_load_ushort v156, v181, s[88:89]
	v_add_u32_e32 v181, 0x1a00, v181
	global_load_ushort v157, v181, s[88:89]
	v_add_u32_e32 v181, 0x1a00, v181
	global_load_ushort v158, v181, s[88:89]
	v_add_u32_e32 v181, 0x1a00, v181
	global_load_ushort v159, v181, s[88:89]
	v_add_u32_e32 v181, 0x1a00, v181
	global_load_ushort v160, v181, s[88:89]
	v_add_u32_e32 v181, 0x1a00, v181
	global_load_ushort v161, v181, s[88:89]
	v_add_u32_e32 v181, 0x1a00, v181
	global_load_ushort v162, v181, s[88:89]
	s_add_i32 s55, s45, 8
	s_min_i32 s55, s55, s46
	s_add_i32 s55, s55, s48
	s_mul_i32 s55, s55, 0x1a00
	v_add_u32_e32 v184, s55, v180
	global_load_ushort v163, v184, s[88:89]
	s_add_i32 s55, s45, 9
	s_min_i32 s55, s55, s46
	s_add_i32 s55, s55, s48
	s_mul_i32 s55, s55, 0x1a00
	v_add_u32_e32 v184, s55, v180
	global_load_ushort v164, v184, s[88:89]
	s_mul_i32 s55, s44, 0x820
	v_lshl_add_u32 v182, v185, 2, s55
	s_mul_i32 s55, s44, 0x480
	v_lshl_add_u32 v183, v185, 1, s55
	s_lshl_b32 s0, s5, 6
	v_and_or_b32 v34, v0, 48, v6
	v_lshlrev_b32_e32 v0, 9, v35
	v_or_b32_e32 v2, s0, v34
	v_ashrrev_i32_e32 v1, 31, v0
	v_lshl_add_u64 v[0:1], v[0:1], 2, s[16:17]
	v_lshlrev_b32_e32 v192, 2, v2
	v_lshl_or_b32 v7, v35, 1, 1
	v_lshl_add_u64 v[2:3], v[0:1], 0, v[192:193]
	v_lshlrev_b32_e32 v0, 8, v7
	v_ashrrev_i32_e32 v1, 31, v0
	v_lshl_add_u64 v[0:1], v[0:1], 2, s[16:17]
	v_lshl_add_u64 v[4:5], v[0:1], 0, v[192:193]
	v_and_b32_e32 v0, 0xffffff00, v29
	v_readlane_b32 s22, v254, 1
	v_lshlrev_b32_e32 v18, 3, v28
	v_ashrrev_i32_e32 v1, 31, v0
	v_readlane_b32 s23, v254, 2
	v_add_u32_e32 v26, s9, v18
	v_and_b32_e32 v31, 63, v29
	v_lshl_add_u64 v[0:1], v[0:1], 2, s[22:23]
	v_lshl_add_u64 v[12:13], v[0:1], 0, v[192:193]
	s_add_i32 s8, s6, -1
	v_or_b32_e32 v30, s0, v31
	v_mov_b64_e32 v[0:1], s[88:89]
	v_lshlrev_b32_e32 v192, 1, v30
	s_add_i32 s7, s4, -1
	s_movk_i32 s21, 0x1000
	v_readlane_b32 s0, v254, 3
	v_lshlrev_b32_e32 v19, 2, v30
	v_readlane_b32 s1, v254, 4
	s_nop 4
	global_load_dword v10, v19, s[0:1] offset:1024
	s_nop 3
	global_load_dword v8, v19, s[0:1] offset:2048
	s_nop 2
	global_load_dword v9, v19, s[0:1] offset:3072
	s_nop 1
	global_load_dword v11, v19, s[0:1]
	global_load_dword v33, v[2:3], off
	global_load_dword v32, v[4:5], off
	global_load_dword v16, v[12:13], off
	s_movk_i32 s22, 0x104
	s_movk_i32 s9, 0x90
	v_or_b32_e32 v49, 7, v26
	v_add_u32_e32 v50, 8, v26
	v_add_u32_e32 v51, 9, v26
	v_ashrrev_i32_e32 v58, 3, v29
	v_min_i32_e32 v38, s7, v51
	v_min_i32_e32 v24, s7, v50
	v_add_u32_e32 v3, s6, v24
	v_mad_i64_i32 v[24:25], s[0:1], v3, s92, v[0:1]
	v_lshl_add_u64 v[24:25], v[24:25], 0, v[192:193]
	v_max_i32_e32 v3, 1, v49
	v_add_co_u32_e64 v24, s[0:1], s21, v24
	v_add_u32_e32 v3, s8, v3
	s_nop 0
	v_addc_co_u32_e64 v25, s[0:1], 0, v25, s[0:1]
	v_mad_u64_u32 v[26:27], s[0:1], v3, s92, v[0:1]
	v_lshl_add_u64 v[26:27], v[26:27], 0, v[192:193]
	v_add_co_u32_e64 v26, s[0:1], s21, v26
	v_add_u32_e32 v3, s6, v49
	s_nop 0
	v_addc_co_u32_e64 v27, s[0:1], 0, v27, s[0:1]
	v_mad_i64_i32 v[36:37], s[0:1], v3, s92, v[0:1]
	v_lshl_add_u64 v[36:37], v[36:37], 0, v[192:193]
	v_add_co_u32_e64 v36, s[0:1], s21, v36
	s_nop 1
	v_addc_co_u32_e64 v37, s[0:1], 0, v37, s[0:1]
	global_load_ushort v56, v[24:25], off offset:1536
	global_load_ushort v57, v[26:27], off offset:1536
	global_load_ushort v37, v[36:37], off offset:1536
	v_add_u32_e32 v12, s6, v38
	v_mad_i64_i32 v[0:1], s[0:1], v12, s92, v[0:1]
	v_lshl_add_u64 v[0:1], v[0:1], 0, v[192:193]
	v_add_co_u32_e64 v0, s[0:1], s21, v0
	v_lshlrev_b32_e32 v12, 4, v29
	s_nop 0
	v_addc_co_u32_e64 v1, s[0:1], 0, v1, s[0:1]
	v_readlane_b32 s0, v254, 5
	v_ashrrev_i32_e32 v36, 7, v29
	s_or_b32 s0, s5, s0
	v_and_b32_e32 v26, 0x70, v12
	v_and_b32_e32 v12, -4, v36
	v_add_u32_e32 v12, s0, v12
	v_ashrrev_i32_e32 v13, 31, v12
	v_readlane_b32 s6, v251, 22
	v_lshlrev_b64 v[12:13], 13, v[12:13]
	v_readlane_b32 s7, v251, 23
	v_lshlrev_b32_e32 v14, 7, v58
	v_and_b32_e32 v192, 0x1f80, v14
	v_lshl_add_u64 v[12:13], s[6:7], 0, v[12:13]
; __device__ __forceinline__ bf16_t f2bf(float f) { return (bf16_t)(pack2(f, 0.f) & 0xffffu); }
; __device__ __forceinline__ float bf2f(bf16_t h) { return __uint_as_float(((unsigned)h) << 16); }
; __device__ void rg_tile(unsigned char* lds, const Params& p, int l, int b, int ck, int hh, bool outmode) {
;     ...
;     const int i = tid & 63, tq = tid >> 6;
;     const int ch = hh * 64 + i;
;     const float* wc = p.in[20] + (size_t)l * 4 * 256 + ch;
;     const float w0 = wc[0], w1 = wc[256], w2 = wc[512], w3 = wc[768];
; #pragma unroll
;     for (int ii = 0; ii < 8; ++ii) {
;       const int tt = tq * 8 + ii;
;       const int tp = t0 + tt;
;       const int tm1 = tp - 1 >= 0 ? tp - 1 : 0, tp1 = tp + 1 < L ? tp + 1 : L - 1, tp2 = tp + 2 < L ? tp + 2 : L - 1;
;       const float z0 = bf2f(z[(size_t)(rowbase + tm1) * ZS + 2816 + ch]);
;       const float z1 = bf2f(z[(size_t)(rowbase + tp) * ZS + 2816 + ch]);
;       const float z2 = bf2f(z[(size_t)(rowbase + tp1) * ZS + 2816 + ch]);
;       const float z3 = bf2f(z[(size_t)(rowbase + tp2) * ZS + 2816 + ch]);
;       float xr = w1 * z1;
;       xr += (tp - 1 >= 0 ? w0 : 0.f) * z0;
;       xr += (tp + 1 < L ? w2 : 0.f) * z2;
;       xr += (tp + 2 < L ? w3 : 0.f) * z3;
;       XR[tt * 65 + i] = xr;
;       XB[tt * 72 + i] = f2bf(xr);
;     }
;     const bf16_t* rgw = (const bf16_t*)(p.ws + OFF_RGW);
; #pragma unroll
;     for (int q = 0; q < 4; ++q) {
;       const int id = tid + 512 * q;
;       const int row = id >> 3, kc = id & 7;
;       *(uint4*)(WT + row * 72 + kc * 8) = *(const uint4*)(rgw + ((size_t)((l * 4 + (row >> 6)) * 4 + hh)) * 4096 + (row & 63) * 64 + kc * 8);
;     }
;   }
;   __syncthreads();
	v_lshl_add_u64 v[12:13], v[12:13], 0, v[192:193]
	v_mov_b32_e32 v27, v193
	v_lshl_add_u64 v[12:13], v[12:13], 0, v[26:27]
	global_load_ushort v59, v[0:1], off offset:1536
	global_load_dwordx4 v[12:15], v[12:13], off
	v_add_u32_e32 v0, 0x200, v29
	v_ashrrev_i32_e32 v60, 3, v0
	v_lshlrev_b32_e32 v18, 7, v60
	v_ashrrev_i32_e32 v0, 7, v0
	v_and_b32_e32 v192, 0x1f80, v18
	v_add_u32_e32 v18, 0x400, v29
	v_and_b32_e32 v0, -4, v0
	v_ashrrev_i32_e32 v61, 3, v18
	v_ashrrev_i32_e32 v18, 7, v18
	v_add_u32_e32 v0, s0, v0
	v_and_b32_e32 v18, -4, v18
	v_ashrrev_i32_e32 v1, 31, v0
	v_add_u32_e32 v18, s0, v18
	v_lshlrev_b64 v[0:1], 13, v[0:1]
	v_ashrrev_i32_e32 v19, 31, v18
	v_lshl_add_u64 v[0:1], s[6:7], 0, v[0:1]
	v_lshlrev_b64 v[18:19], 13, v[18:19]
	v_lshlrev_b32_e32 v20, 7, v61
	v_lshl_add_u64 v[0:1], v[0:1], 0, v[192:193]
	v_lshl_add_u64 v[18:19], s[6:7], 0, v[18:19]
	v_and_b32_e32 v192, 0x1f80, v20
	v_lshl_add_u64 v[18:19], v[18:19], 0, v[192:193]
	v_lshl_add_u64 v[0:1], v[0:1], 0, v[26:27]
	v_lshl_add_u64 v[22:23], v[18:19], 0, v[26:27]
	global_load_dwordx4 v[18:21], v[0:1], off
	global_load_dwordx4 v[22:25], v[22:23], off
	v_add_u32_e32 v0, 0x600, v29
	v_ashrrev_i32_e32 v62, 3, v0
	v_ashrrev_i32_e32 v0, 7, v0
	v_and_b32_e32 v0, -4, v0
	v_add_u32_e32 v0, s0, v0
	v_ashrrev_i32_e32 v1, 31, v0
	v_lshlrev_b64 v[0:1], 13, v[0:1]
	v_lshlrev_b32_e32 v38, 7, v62
	v_lshl_add_u64 v[0:1], s[6:7], 0, v[0:1]
	v_and_b32_e32 v192, 0x1f80, v38
	v_lshl_add_u64 v[0:1], v[0:1], 0, v[192:193]
	v_lshl_add_u64 v[0:1], v[0:1], 0, v[26:27]
	global_load_dwordx4 v[38:41], v[0:1], off
	v_cmp_gt_i32_e32 vcc, s4, v50
	s_waitcnt vmcnt(0)
	v_lshlrev_b32_e32 v27, 16, v56
	v_lshlrev_b32_e32 v1, 16, v37
	v_cmp_lt_i32_e64 s[0:1], 0, v49
	v_lshlrev_b32_e32 v0, 16, v57
	v_mul_f32_e32 v1, v10, v1
	v_cndmask_b32_e64 v5, 0, v11, s[0:1]
	v_fmac_f32_e32 v1, v5, v0
	v_cndmask_b32_e32 v0, 0, v8, vcc
	v_cmp_gt_i32_e32 vcc, s4, v51
	v_lshlrev_b32_e32 v3, 16, v59
	v_fmac_f32_e32 v1, v0, v27
	v_cndmask_b32_e32 v0, 0, v9, vcc
	v_fmac_f32_e32 v1, v0, v3
	v_add_u32_e32 v0, 0, v26
	v_mad_u64_u32 v[2:3], s[0:1], v58, s9, v[0:1]
	ds_write_b128 v2, v[12:15] offset:25856
	v_mad_u64_u32 v[2:3], s[0:1], v60, s9, v[0:1]
	ds_write_b128 v2, v[18:21] offset:25856
	v_mad_u64_u32 v[2:3], s[0:1], v61, s9, v[0:1]
	v_mad_u64_u32 v[0:1], s[0:1], v62, s9, v[0:1]
	ds_write_b128 v2, v[22:25] offset:25856
	ds_write_b128 v0, v[38:41] offset:25856
	v_and_b32_e32 v0, 48, v29
	v_add_u32_e32 v0, 0, v0
	v_mad_u32_u24 v17, v6, s9, v0
	s_waitcnt vmcnt(0)
	v_lshlrev_b32_e32 v154, 16, v154
	v_lshlrev_b32_e32 v155, 16, v155
	v_lshlrev_b32_e32 v156, 16, v156
	v_lshlrev_b32_e32 v157, 16, v157
	v_lshlrev_b32_e32 v158, 16, v158
	v_lshlrev_b32_e32 v159, 16, v159
	v_lshlrev_b32_e32 v160, 16, v160
	v_lshlrev_b32_e32 v161, 16, v161
	v_lshlrev_b32_e32 v162, 16, v162
	v_lshlrev_b32_e32 v163, 16, v163
	v_lshlrev_b32_e32 v164, 16, v164
	s_cmp_ge_i32 s45, 1
	s_cselect_b64 s[56:57], -1, 0
	s_add_i32 s55, s45, 8
	s_cmp_lt_i32 s55, s47
	s_cselect_b64 s[58:59], -1, 0
	v_cndmask_b32_e64 v169, 0, v165, s[56:57]
	v_cndmask_b32_e64 v170, 0, v167, s[58:59]
	v_cndmask_b32_e64 v171, 0, v168, s[58:59]
	v_mul_f32_e32 v172, v166, v155
	v_fmac_f32_e32 v172, v169, v154
	v_fmac_f32_e32 v172, v167, v156
	v_fmac_f32_e32 v172, v168, v157
	v_mul_f32_e32 v173, v166, v156
	v_fmac_f32_e32 v173, v165, v155
	v_fmac_f32_e32 v173, v167, v157
	v_fmac_f32_e32 v173, v168, v158
	v_mul_f32_e32 v174, v166, v157
	v_fmac_f32_e32 v174, v165, v156
	v_fmac_f32_e32 v174, v167, v158
	v_fmac_f32_e32 v174, v168, v159
	v_mul_f32_e32 v175, v166, v158
	v_fmac_f32_e32 v175, v165, v157
	v_fmac_f32_e32 v175, v167, v159
	v_fmac_f32_e32 v175, v168, v160
	v_mul_f32_e32 v176, v166, v159
	v_fmac_f32_e32 v176, v165, v158
	v_fmac_f32_e32 v176, v167, v160
	v_fmac_f32_e32 v176, v168, v161
	v_mul_f32_e32 v177, v166, v160
	v_fmac_f32_e32 v177, v165, v159
	v_fmac_f32_e32 v177, v167, v161
	v_fmac_f32_e32 v177, v168, v162
	v_mul_f32_e32 v178, v166, v161
	v_fmac_f32_e32 v178, v165, v160
	v_fmac_f32_e32 v178, v167, v162
	v_fmac_f32_e32 v178, v171, v163
	v_mul_f32_e32 v179, v166, v162
	v_fmac_f32_e32 v179, v165, v161
	v_fmac_f32_e32 v179, v170, v163
	v_fmac_f32_e32 v179, v171, v164
	v_cvt_pk_bf16_f32 v184, v172, v172
	ds_write_b32 v182, v172
	ds_write_b16 v183, v184 offset:16640
	v_cvt_pk_bf16_f32 v184, v173, v173
	ds_write_b32 v182, v173 offset:260
	ds_write_b16 v183, v184 offset:16784
	v_cvt_pk_bf16_f32 v184, v174, v174
	ds_write_b32 v182, v174 offset:520
	ds_write_b16 v183, v184 offset:16928
	v_cvt_pk_bf16_f32 v184, v175, v175
	ds_write_b32 v182, v175 offset:780
	ds_write_b16 v183, v184 offset:17072
	v_cvt_pk_bf16_f32 v184, v176, v176
	ds_write_b32 v182, v176 offset:1040
	ds_write_b16 v183, v184 offset:17216
	v_cvt_pk_bf16_f32 v184, v177, v177
	ds_write_b32 v182, v177 offset:1300
	ds_write_b16 v183, v184 offset:17360
	v_cvt_pk_bf16_f32 v184, v178, v178
	ds_write_b32 v182, v178 offset:1560
	ds_write_b16 v183, v184 offset:17504
	v_cvt_pk_bf16_f32 v184, v179, v179
	ds_write_b32 v182, v179 offset:1820
	ds_write_b16 v183, v184 offset:17648
	s_waitcnt lgkmcnt(0)
	s_barrier
; __device__ __forceinline__ float fexp(float x) { return __expf(x); }
; __device__ __forceinline__ float sigm(float x) { return frcp(1.f + fexp(-x)); }
; __device__ __forceinline__ float softplusf(float x) { return fmaxf(x, 0.f) + __logf(1.f + fexp(-fabsf(x))); }
; __device__ void rg_tile(unsigned char* lds, const Params& p, int l, int b, int ck, int hh, bool outmode) {
;     ...
;   {
;     const int d = w >> 2, jf = w & 3;
;     f32x4 ar[4], ai[4];
; #pragma unroll
;     for (int i = 0; i < 4; ++i) { ar[i] = (f32x4){0.f, 0.f, 0.f, 0.f}; ai[i] = (f32x4){0.f, 0.f, 0.f, 0.f}; }
; #pragma unroll
;     for (int ks = 0; ks < 2; ++ks) {
;       const bf16x8 wr = ldfrag(WT + ((d * 2 + 0) * 64 + jf * 16 + lr) * 72 + ks * 32 + lg * 8);
;       const bf16x8 wi = ldfrag(WT + ((d * 2 + 1) * 64 + jf * 16 + lr) * 72 + ks * 32 + lg * 8);
; #pragma unroll
;       for (int tf = 0; tf < 4; ++tf) {
;         const bf16x8 xf = ldfrag(XB + (tf * 16 + lr) * 72 + ks * 32 + lg * 8);
;         ar[tf] = mfma16(xf, wr, ar[tf]);
;         ai[tf] = mfma16(xf, wi, ai[tf]);
;       }
;     }
;     const int j = jf * 16 + lr;
;     const int ch = hh * 64 + j;
;     const float sp = softplusf(-lam_);
; #pragma unroll
;     for (int tf = 0; tf < 4; ++tf)
; #pragma unroll
;       for (int jj = 0; jj < 4; ++jj) {
;         const int tt = tf * 16 + lg * 4 + jj;
;         const float r = sigm(ar[tf][jj] + br);
;         const float ig = sigm(ai[tf][jj] + bi);
;         const float la = -8.0f * r * sp;
;         const float a = fexp(la);
;         const float bq = __builtin_amdgcn_sqrtf(fmaxf(1.f - a * a, 0.f)) * ig * XR[tt * 65 + j];
;         AA[(d * 64 + tt) * 64 + j] = a;
;         BQ[(d * 64 + tt) * 64 + j] = bq;
;       }
	ds_read_b128 v[18:21], v17 offset:16640
	v_lshl_or_b32 v1, v35, 7, v34
	v_mad_u64_u32 v[2:3], s[0:1], v1, s9, v[0:1]
	v_lshl_or_b32 v1, v7, 6, v34
	ds_read_b128 v[12:15], v2 offset:25856
	v_mad_u64_u32 v[0:1], s[0:1], v1, s9, v[0:1]
	ds_read_b128 v[4:7], v2 offset:25920
	ds_read_b128 v[22:25], v17 offset:16704
	ds_read_b128 v[8:11], v0 offset:25856
	ds_read_b128 v[0:3], v0 offset:25920
	s_mov_b32 s0, 0xbfb8aa3b
	v_mul_f32_e64 v26, |v16|, s0
	s_waitcnt lgkmcnt(4)
	v_mfma_f32_16x16x32_bf16 v[38:41], v[18:21], v[12:15], 0
	v_exp_f32_e32 v26, v26
	s_mov_b32 s0, 0x800000
	v_max_f32_e64 v16, -v16, -v16
	s_waitcnt lgkmcnt(1)
	v_mfma_f32_16x16x32_bf16 v[18:21], v[18:21], v[8:11], 0
	v_max_f32_e32 v16, 0, v16
	v_bfe_u32 v62, v29, 4, 2
	ds_read_b128 v[42:45], v17 offset:18944
	ds_read_b128 v[46:49], v17 offset:19008
	s_waitcnt lgkmcnt(2)
	v_mfma_f32_16x16x32_bf16 v[54:57], v[22:25], v[0:3], v[18:21]
	v_lshlrev_b32_e32 v35, 12, v35
	s_nop 1
	v_add_f32_e32 v18, 1.0, v26
	v_cmp_gt_f32_e32 vcc, s0, v18
	v_mfma_f32_16x16x32_bf16 v[38:41], v[22:25], v[4:7], v[38:41]
	s_mov_b32 s0, 0x3f317217
	v_cndmask_b32_e64 v19, 0, 32, vcc
	v_ldexp_f32 v18, v18, v19
	v_log_f32_e32 v18, v18
	v_mov_b32_e32 v20, 0x41b17218
	v_cndmask_b32_e32 v20, 0, v20, vcc
	s_nop 1
	v_add_f32_e32 v39, v33, v39
	v_mul_f32_e32 v19, 0x3f317217, v18
	v_fma_f32 v19, v18, s0, -v19
	v_fmac_f32_e32 v19, 0x3377d1cf, v18
	s_mov_b32 s0, 0x7f800000
	v_fmac_f32_e32 v19, 0x3f317217, v18
	v_cmp_lt_f32_e64 s[0:1], |v18|, s0
	ds_read_b128 v[58:61], v17 offset:21248
	ds_read_b128 v[24:27], v17 offset:21312
	v_cndmask_b32_e64 v18, v18, v19, s[0:1]
	v_add_f32_e32 v19, v33, v38
	v_mul_f32_e32 v19, 0xbfb8aa3b, v19
	v_exp_f32_e32 v19, v19
	v_sub_f32_e32 v18, v18, v20
	v_add_f32_e32 v37, v16, v18
	v_add_f32_e32 v18, v32, v54
	v_add_f32_e32 v16, 1.0, v19
	v_rcp_f32_e32 v16, v16
	v_mul_f32_e32 v18, 0xbfb8aa3b, v18
	v_exp_f32_e32 v18, v18
	v_lshl_add_u32 v54, v34, 2, 0
	v_mul_f32_e32 v16, 0xc1000000, v16
	v_mul_f32_e32 v16, v37, v16
	v_mul_f32_e32 v16, 0x3fb8aa3b, v16
	v_exp_f32_e32 v38, v16
	v_add_f32_e32 v16, 1.0, v18
	v_rcp_f32_e32 v63, v16
	s_movk_i32 s0, 0x410
	v_fma_f32 v16, -v38, v38, 1.0
	v_max_f32_e32 v16, 0, v16
	v_sqrt_f32_e32 v64, v16
	v_mad_u32_u24 v16, v62, s0, v54
	ds_read_b32 v65, v16
	ds_read_b128 v[20:23], v17 offset:23552
	ds_read_b128 v[16:19], v17 offset:23616
	v_mul_f32_e32 v39, 0xbfb8aa3b, v39
	v_mul_f32_e32 v63, v63, v64
	v_lshlrev_b32_e32 v64, 8, v62
	v_or3_b32 v64, v64, v35, v34
	v_exp_f32_e32 v39, v39
	v_lshlrev_b32_e32 v64, 2, v64
	s_waitcnt lgkmcnt(2)
	v_mul_f32_e32 v63, v65, v63
	v_add_u32_e32 v65, 0, v64
	v_readlane_b32 s0, v253, 37
	ds_write_b32 v65, v38 offset:62720
	v_mfma_f32_16x16x32_bf16 v[50:53], v[42:45], v[12:15], 0
	v_add_u32_e32 v38, s0, v64
	ds_write_b32 v38, v63
	v_add_f32_e32 v38, 1.0, v39
	v_add_f32_e32 v39, v32, v55
	v_lshl_or_b32 v55, v62, 2, 1
	v_rcp_f32_e32 v38, v38
	v_mad_u32_u24 v54, v55, s22, v54
	v_lshlrev_b32_e32 v55, 6, v55
	v_or3_b32 v34, v55, v35, v34
	v_add_f32_e32 v35, v33, v40
	v_mul_f32_e32 v35, 0xbfb8aa3b, v35
	v_exp_f32_e32 v35, v35
	v_mul_f32_e32 v38, 0xc1000000, v38
	v_mul_f32_e32 v38, v37, v38
	v_mul_f32_e32 v38, 0x3fb8aa3b, v38
	v_mul_f32_e32 v39, 0xbfb8aa3b, v39
	v_exp_f32_e32 v38, v38
	v_add_f32_e32 v35, 1.0, v35
	v_exp_f32_e32 v39, v39
	v_rcp_f32_e32 v35, v35
	v_fma_f32 v62, -v38, v38, 1.0
	v_lshlrev_b32_e32 v34, 2, v34
	v_add_f32_e32 v39, 1.0, v39
	v_max_f32_e32 v62, 0, v62
	v_add_u32_e32 v40, 0, v34
	v_mul_f32_e32 v35, 0xc1000000, v35
	v_rcp_f32_e32 v39, v39
	v_sqrt_f32_e32 v62, v62
	ds_read_b32 v63, v54
	ds_write_b32 v40, v38 offset:62720
	v_add_f32_e32 v38, v32, v56
	v_mul_f32_e32 v35, v37, v35
	v_mul_f32_e32 v38, 0xbfb8aa3b, v38
	v_mul_f32_e32 v35, 0x3fb8aa3b, v35
	v_exp_f32_e32 v38, v38
	v_exp_f32_e32 v35, v35
	v_mul_f32_e32 v39, v39, v62
	s_waitcnt lgkmcnt(1)
	v_mul_f32_e32 v39, v63, v39
	v_add_u32_e32 v34, s0, v34
	ds_write_b32 v34, v39
	v_add_f32_e32 v34, 1.0, v38
	v_fma_f32 v38, -v35, v35, 1.0
	v_max_f32_e32 v38, 0, v38
	v_rcp_f32_e32 v34, v34
	v_sqrt_f32_e32 v38, v38
	ds_read_b32 v39, v54 offset:260
	v_mfma_f32_16x16x32_bf16 v[42:45], v[42:45], v[8:11], 0
	v_mul_f32_e32 v34, v34, v38
	v_or_b32_e32 v38, 0x200, v64
	s_waitcnt lgkmcnt(0)
	v_mul_f32_e32 v34, v34, v39
	v_add_f32_e32 v39, v33, v41
	v_mul_f32_e32 v39, 0xbfb8aa3b, v39
	v_exp_f32_e32 v39, v39
	v_add_u32_e32 v40, 0, v38
	ds_write_b32 v40, v35 offset:62720
	v_add_u32_e32 v35, s0, v38
	v_add_f32_e32 v38, 1.0, v39
	v_rcp_f32_e32 v38, v38
	v_add_f32_e32 v39, v32, v57
	v_mul_f32_e32 v39, 0xbfb8aa3b, v39
	v_mfma_f32_16x16x32_bf16 v[50:53], v[46:49], v[4:7], v[50:53]
	v_exp_f32_e32 v39, v39
	v_mul_f32_e32 v38, 0xc1000000, v38
	v_mul_f32_e32 v38, v37, v38
	v_mul_f32_e32 v38, 0x3fb8aa3b, v38
	v_exp_f32_e32 v55, v38
	ds_write_b32 v35, v34
	v_add_f32_e32 v34, 1.0, v39
	v_mfma_f32_16x16x32_bf16 v[38:41], v[46:49], v[0:3], v[42:45]
	v_fma_f32 v35, -v55, v55, 1.0
	v_max_f32_e32 v35, 0, v35
	v_rcp_f32_e32 v34, v34
	v_add_f32_e32 v42, v33, v50
	v_mul_f32_e32 v42, 0xbfb8aa3b, v42
	v_exp_f32_e32 v42, v42
	v_sqrt_f32_e32 v35, v35
	ds_read_b32 v56, v54 offset:520
	v_add_f32_e32 v38, v32, v38
	v_add_f32_e32 v42, 1.0, v42
	v_rcp_f32_e32 v42, v42
	v_mul_f32_e32 v38, 0xbfb8aa3b, v38
	v_exp_f32_e32 v38, v38
	v_mul_f32_e32 v34, v34, v35
	v_mul_f32_e32 v42, 0xc1000000, v42
	v_mul_f32_e32 v42, v37, v42
	v_mul_f32_e32 v42, 0x3fb8aa3b, v42
	v_exp_f32_e32 v46, v42
	v_or_b32_e32 v35, 0x300, v64
	s_waitcnt lgkmcnt(0)
; __device__ __forceinline__ float fexp(float x) { return __expf(x); }
; __device__ __forceinline__ float sigm(float x) { return frcp(1.f + fexp(-x)); }
; __device__ void rg_tile(unsigned char* lds, const Params& p, int l, int b, int ck, int hh, bool outmode) {
;     ...
; #pragma unroll
;     for (int tf = 0; tf < 4; ++tf)
; #pragma unroll
;       for (int jj = 0; jj < 4; ++jj) {
;         const int tt = tf * 16 + lg * 4 + jj;
;         const float r = sigm(ar[tf][jj] + br);
;         const float ig = sigm(ai[tf][jj] + bi);
;         const float la = -8.0f * r * sp;
;         const float a = fexp(la);
;         const float bq = __builtin_amdgcn_sqrtf(fmaxf(1.f - a * a, 0.f)) * ig * XR[tt * 65 + j];
;         AA[(d * 64 + tt) * 64 + j] = a;
;         BQ[(d * 64 + tt) * 64 + j] = bq;
;       }
	v_mul_f32_e32 v34, v34, v56
	v_add_u32_e32 v43, 0, v35
	v_add_u32_e32 v35, s0, v35
	ds_write_b32 v35, v34
	v_fma_f32 v35, -v46, v46, 1.0
	ds_write_b32 v43, v55 offset:62720
	v_add_f32_e32 v34, 1.0, v38
	v_max_f32_e32 v35, 0, v35
	v_rcp_f32_e32 v34, v34
	v_sqrt_f32_e32 v35, v35
	ds_read_b32 v38, v54 offset:3900
	v_add_f32_e32 v39, v32, v39
	v_mul_f32_e32 v39, 0xbfb8aa3b, v39
	v_mul_f32_e32 v34, v34, v35
	v_exp_f32_e32 v39, v39
	s_waitcnt lgkmcnt(0)
	v_mul_f32_e32 v34, v34, v38
	v_add_f32_e32 v38, v33, v51
	v_mul_f32_e32 v38, 0xbfb8aa3b, v38
	v_exp_f32_e32 v38, v38
	v_or_b32_e32 v35, 0x1000, v64
	v_add_u32_e32 v47, 0, v35
	v_add_u32_e32 v35, s0, v35
	v_add_f32_e32 v38, 1.0, v38
	v_rcp_f32_e32 v38, v38
	ds_write_b32 v35, v34
	ds_write_b32 v47, v46 offset:62720
	v_add_f32_e32 v34, 1.0, v39
	v_mul_f32_e32 v38, 0xc1000000, v38
	v_mul_f32_e32 v38, v37, v38
	v_mul_f32_e32 v38, 0x3fb8aa3b, v38
	v_exp_f32_e32 v38, v38
	v_rcp_f32_e32 v34, v34
	ds_read_b32 v39, v54 offset:4160
	v_mfma_f32_16x16x32_bf16 v[42:45], v[58:61], v[12:15], 0
	v_fma_f32 v35, -v38, v38, 1.0
	v_max_f32_e32 v35, 0, v35
	v_sqrt_f32_e32 v35, v35
	v_mfma_f32_16x16x32_bf16 v[42:45], v[24:27], v[4:7], v[42:45]
	v_mul_f32_e32 v34, v34, v35
	s_waitcnt lgkmcnt(0)
	v_mul_f32_e32 v34, v34, v39
	v_add_f32_e32 v39, v33, v52
	v_mul_f32_e32 v39, 0xbfb8aa3b, v39
	v_exp_f32_e32 v39, v39
	v_or_b32_e32 v35, 0x1100, v64
	v_add_u32_e32 v50, 0, v35
	ds_write_b32 v50, v38 offset:62720
	v_add_f32_e32 v38, 1.0, v39
	v_rcp_f32_e32 v38, v38
	v_add_f32_e32 v39, v32, v40
	v_mul_f32_e32 v39, 0xbfb8aa3b, v39
	v_exp_f32_e32 v39, v39
	v_mul_f32_e32 v38, 0xc1000000, v38
	v_mul_f32_e32 v38, v37, v38
	v_mul_f32_e32 v38, 0x3fb8aa3b, v38
	v_exp_f32_e32 v38, v38
	v_add_u32_e32 v35, s0, v35
	ds_write_b32 v35, v34
	v_add_f32_e32 v34, 1.0, v39
	v_fma_f32 v35, -v38, v38, 1.0
	v_max_f32_e32 v35, 0, v35
	v_rcp_f32_e32 v34, v34
	v_sqrt_f32_e32 v35, v35
	ds_read_b32 v39, v54 offset:4420
	v_mfma_f32_16x16x32_bf16 v[46:49], v[58:61], v[8:11], 0
	v_mul_f32_e32 v34, v34, v35
	v_or_b32_e32 v35, 0x1200, v64
	s_waitcnt lgkmcnt(0)
	v_mul_f32_e32 v34, v34, v39
	v_add_f32_e32 v39, v33, v53
	v_mul_f32_e32 v39, 0xbfb8aa3b, v39
	v_exp_f32_e32 v39, v39
	v_add_u32_e32 v40, 0, v35
	ds_write_b32 v40, v38 offset:62720
	v_add_u32_e32 v35, s0, v35
	v_add_f32_e32 v38, 1.0, v39
	v_rcp_f32_e32 v38, v38
	v_add_f32_e32 v39, v32, v41
	v_mul_f32_e32 v39, 0xbfb8aa3b, v39
	v_exp_f32_e32 v39, v39
	v_mul_f32_e32 v38, 0xc1000000, v38
	v_mul_f32_e32 v38, v37, v38
	v_mul_f32_e32 v38, 0x3fb8aa3b, v38
	v_exp_f32_e32 v38, v38
	ds_write_b32 v35, v34
	v_add_f32_e32 v34, 1.0, v39
	v_rcp_f32_e32 v34, v34
	v_fma_f32 v35, -v38, v38, 1.0
	v_max_f32_e32 v35, 0, v35
	v_sqrt_f32_e32 v35, v35
	ds_read_b32 v39, v54 offset:4680
	v_mfma_f32_16x16x32_bf16 v[24:27], v[24:27], v[0:3], v[46:49]
	v_mul_f32_e32 v34, v34, v35
	v_or_b32_e32 v35, 0x1300, v64
	s_waitcnt lgkmcnt(0)
	v_mul_f32_e32 v34, v34, v39
	v_add_f32_e32 v39, v33, v42
	v_mul_f32_e32 v39, 0xbfb8aa3b, v39
	v_exp_f32_e32 v39, v39
	v_add_u32_e32 v40, 0, v35
	ds_write_b32 v40, v38 offset:62720
	v_add_f32_e32 v24, v32, v24
	v_add_f32_e32 v38, 1.0, v39
	v_rcp_f32_e32 v38, v38
	v_mul_f32_e32 v24, 0xbfb8aa3b, v24
	v_exp_f32_e32 v24, v24
	v_add_u32_e32 v35, s0, v35
	v_mul_f32_e32 v38, 0xc1000000, v38
	v_mul_f32_e32 v38, v37, v38
	v_mul_f32_e32 v38, 0x3fb8aa3b, v38
	v_exp_f32_e32 v38, v38
	ds_write_b32 v35, v34
	v_add_f32_e32 v24, 1.0, v24
	v_rcp_f32_e32 v24, v24
	v_fma_f32 v34, -v38, v38, 1.0
	v_max_f32_e32 v34, 0, v34
	v_sqrt_f32_e32 v34, v34
	ds_read_b32 v35, v54 offset:8060
	v_mfma_f32_16x16x32_bf16 v[12:15], v[20:23], v[12:15], 0
	v_add_f32_e32 v25, v32, v25
	v_mul_f32_e32 v24, v24, v34
	v_mul_f32_e32 v25, 0xbfb8aa3b, v25
	s_waitcnt lgkmcnt(0)
	v_mul_f32_e32 v24, v24, v35
	v_add_f32_e32 v35, v33, v43
	v_mul_f32_e32 v35, 0xbfb8aa3b, v35
	v_exp_f32_e32 v35, v35
	v_mfma_f32_16x16x32_bf16 v[8:11], v[20:23], v[8:11], 0
	v_add_f32_e32 v22, v33, v44
	v_mul_f32_e32 v22, 0xbfb8aa3b, v22
	v_add_f32_e32 v35, 1.0, v35
	v_rcp_f32_e32 v35, v35
	v_exp_f32_e32 v22, v22
	v_exp_f32_e32 v25, v25
	v_or_b32_e32 v34, 0x2000, v64
	v_mul_f32_e32 v35, 0xc1000000, v35
	v_mul_f32_e32 v35, v37, v35
	v_mul_f32_e32 v35, 0x3fb8aa3b, v35
	v_exp_f32_e32 v35, v35
	v_add_f32_e32 v22, 1.0, v22
	v_rcp_f32_e32 v22, v22
	v_mfma_f32_16x16x32_bf16 v[4:7], v[16:19], v[4:7], v[12:15]
	v_add_u32_e32 v39, 0, v34
	v_add_u32_e32 v34, s0, v34
	ds_write_b32 v34, v24
	v_add_f32_e32 v14, v33, v45
	v_mul_f32_e32 v14, 0xbfb8aa3b, v14
	v_add_f32_e32 v24, 1.0, v25
	v_fma_f32 v25, -v35, v35, 1.0
	v_exp_f32_e32 v14, v14
	ds_write_b32 v39, v38 offset:62720
	v_max_f32_e32 v25, 0, v25
	v_or_b32_e32 v21, 0x2100, v64
	v_mul_f32_e32 v22, 0xc1000000, v22
	v_rcp_f32_e32 v24, v24
	v_sqrt_f32_e32 v25, v25
	ds_read_b32 v34, v54 offset:8320
	v_add_u32_e32 v23, 0, v21
	v_mul_f32_e32 v22, v37, v22
	ds_write_b32 v23, v35 offset:62720
	v_add_f32_e32 v23, v32, v26
	v_mul_f32_e32 v22, 0x3fb8aa3b, v22
	v_mul_f32_e32 v23, 0xbfb8aa3b, v23
	v_exp_f32_e32 v22, v22
	v_add_f32_e32 v14, 1.0, v14
	v_exp_f32_e32 v23, v23
	v_rcp_f32_e32 v14, v14
	v_mul_f32_e32 v20, v24, v25
	v_add_f32_e32 v4, v33, v4
	s_waitcnt lgkmcnt(1)
	v_mul_f32_e32 v20, v20, v34
	v_add_u32_e32 v21, s0, v21
	v_mul_f32_e32 v4, 0xbfb8aa3b, v4
	ds_write_b32 v21, v20
	v_fma_f32 v21, -v22, v22, 1.0
	v_exp_f32_e32 v4, v4
	v_add_f32_e32 v20, 1.0, v23
	v_max_f32_e32 v21, 0, v21
	v_or_b32_e32 v13, 0x2200, v64
	v_mul_f32_e32 v14, 0xc1000000, v14
	v_rcp_f32_e32 v20, v20
	v_sqrt_f32_e32 v21, v21
	ds_read_b32 v23, v54 offset:8580
	v_add_u32_e32 v15, 0, v13
	v_mul_f32_e32 v14, v37, v14
	ds_write_b32 v15, v22 offset:62720
	v_add_f32_e32 v15, v32, v27
	v_mul_f32_e32 v14, 0x3fb8aa3b, v14
	v_mul_f32_e32 v15, 0xbfb8aa3b, v15
	v_exp_f32_e32 v14, v14
	v_add_f32_e32 v4, 1.0, v4
	v_exp_f32_e32 v15, v15
	v_rcp_f32_e32 v4, v4
	v_mul_f32_e32 v12, v20, v21
	s_waitcnt lgkmcnt(1)
; __device__ __forceinline__ float fexp(float x) { return __expf(x); }
; __device__ __forceinline__ float sigm(float x) { return frcp(1.f + fexp(-x)); }
; __device__ void rg_tile(unsigned char* lds, const Params& p, int l, int b, int ck, int hh, bool outmode) {
;     ...
; #pragma unroll
;     for (int tf = 0; tf < 4; ++tf)
; #pragma unroll
;       for (int jj = 0; jj < 4; ++jj) {
;         const int tt = tf * 16 + lg * 4 + jj;
;         const float r = sigm(ar[tf][jj] + br);
;         const float ig = sigm(ai[tf][jj] + bi);
;         const float la = -8.0f * r * sp;
;         const float a = fexp(la);
;         const float bq = __builtin_amdgcn_sqrtf(fmaxf(1.f - a * a, 0.f)) * ig * XR[tt * 65 + j];
;         AA[(d * 64 + tt) * 64 + j] = a;
;         BQ[(d * 64 + tt) * 64 + j] = bq;
;       }
;   }
;   __syncthreads();
;   {
;     float* SEG = XR;
;     const int seg = tid >> 7, d = (tid >> 6) & 1, j = tid & 63;
;     const int ch = hh * 64 + j;
;     const size_t ci = ((size_t)(b * 36 + ck) * 2 + d) * 256 + ch;
;     float H = 0.f, Ap = 1.f;
; #pragma unroll
;     for (int q = 0; q < 16; ++q) {
;       const int pos = seg * 16 + q;
;       const int tt = d == 0 ? pos : 63 - pos;
	v_mul_f32_e32 v12, v12, v23
	v_add_u32_e32 v13, s0, v13
	v_mfma_f32_16x16x32_bf16 v[0:3], v[16:19], v[0:3], v[8:11]
	v_add_f32_e32 v5, v33, v5
	ds_write_b32 v13, v12
	v_fma_f32 v13, -v14, v14, 1.0
	v_mul_f32_e32 v5, 0xbfb8aa3b, v5
	v_add_f32_e32 v12, 1.0, v15
	v_max_f32_e32 v13, 0, v13
	v_mul_f32_e32 v4, 0xc1000000, v4
	v_exp_f32_e32 v5, v5
	v_rcp_f32_e32 v12, v12
	v_sqrt_f32_e32 v13, v13
	ds_read_b32 v15, v54 offset:8840
	v_mul_f32_e32 v4, v37, v4
	v_add_f32_e32 v0, v32, v0
	v_mul_f32_e32 v4, 0x3fb8aa3b, v4
	v_mul_f32_e32 v0, 0xbfb8aa3b, v0
	v_exp_f32_e32 v4, v4
	v_exp_f32_e32 v0, v0
	v_add_f32_e32 v5, 1.0, v5
	v_mul_f32_e32 v8, v12, v13
	v_or_b32_e32 v9, 0x2300, v64
	v_rcp_f32_e32 v5, v5
	s_waitcnt lgkmcnt(0)
	v_mul_f32_e32 v8, v8, v15
	v_add_u32_e32 v10, 0, v9
	v_add_u32_e32 v9, s0, v9
	ds_write_b32 v9, v8
	v_fma_f32 v8, -v4, v4, 1.0
	ds_write_b32 v10, v14 offset:62720
	v_add_f32_e32 v0, 1.0, v0
	v_max_f32_e32 v8, 0, v8
	v_rcp_f32_e32 v0, v0
	v_sqrt_f32_e32 v8, v8
	ds_read_b32 v9, v54 offset:12220
	v_mul_f32_e32 v5, 0xc1000000, v5
	v_add_f32_e32 v1, v32, v1
	v_mul_f32_e32 v5, v37, v5
	v_mul_f32_e32 v1, 0xbfb8aa3b, v1
	v_mul_f32_e32 v5, 0x3fb8aa3b, v5
	v_exp_f32_e32 v1, v1
	v_exp_f32_e32 v5, v5
	v_mul_f32_e32 v0, v0, v8
	v_or_b32_e32 v8, 0x3000, v64
	s_waitcnt lgkmcnt(0)
	v_mul_f32_e32 v0, v0, v9
	v_add_u32_e32 v9, 0, v8
	ds_write_b32 v9, v4 offset:62720
	v_add_u32_e32 v4, s0, v8
	ds_write_b32 v4, v0
	v_add_f32_e32 v0, 1.0, v1
	v_fma_f32 v1, -v5, v5, 1.0
	v_max_f32_e32 v1, 0, v1
	v_rcp_f32_e32 v0, v0
	v_sqrt_f32_e32 v1, v1
	ds_read_b32 v4, v54 offset:12480
	v_add_f32_e32 v2, v32, v2
	v_mul_f32_e32 v2, 0xbfb8aa3b, v2
	v_mul_f32_e32 v0, v0, v1
	v_exp_f32_e32 v2, v2
	s_waitcnt lgkmcnt(0)
	v_mul_f32_e32 v0, v0, v4
	v_add_f32_e32 v4, v33, v6
	v_mul_f32_e32 v4, 0xbfb8aa3b, v4
	v_exp_f32_e32 v4, v4
	v_or_b32_e32 v1, 0x3100, v64
	v_add_u32_e32 v6, 0, v1
	v_add_u32_e32 v1, s0, v1
	v_add_f32_e32 v4, 1.0, v4
	v_rcp_f32_e32 v4, v4
	ds_write_b32 v1, v0
	ds_write_b32 v6, v5 offset:62720
	v_add_f32_e32 v0, 1.0, v2
	v_mul_f32_e32 v4, 0xc1000000, v4
	v_mul_f32_e32 v4, v37, v4
	v_mul_f32_e32 v4, 0x3fb8aa3b, v4
	v_exp_f32_e32 v4, v4
	v_rcp_f32_e32 v0, v0
	ds_read_b32 v2, v54 offset:12740
	v_add_f32_e32 v3, v32, v3
	v_fma_f32 v1, -v4, v4, 1.0
	v_max_f32_e32 v1, 0, v1
	v_sqrt_f32_e32 v1, v1
	v_mul_f32_e32 v3, 0xbfb8aa3b, v3
	v_exp_f32_e32 v3, v3
	v_lshlrev_b32_e32 v15, 4, v36
	v_mul_f32_e32 v0, v0, v1
	s_waitcnt lgkmcnt(0)
	v_mul_f32_e32 v0, v0, v2
	v_add_f32_e32 v2, v33, v7
	v_mul_f32_e32 v2, 0xbfb8aa3b, v2
	v_exp_f32_e32 v2, v2
	v_or_b32_e32 v1, 0x3200, v64
	v_add_u32_e32 v5, 0, v1
	v_add_u32_e32 v1, s0, v1
	v_add_f32_e32 v2, 1.0, v2
	v_rcp_f32_e32 v2, v2
	ds_write_b32 v1, v0
	ds_write_b32 v5, v4 offset:62720
	v_add_f32_e32 v0, 1.0, v3
	v_mul_f32_e32 v2, 0xc1000000, v2
	v_mul_f32_e32 v2, v37, v2
	v_mul_f32_e32 v2, 0x3fb8aa3b, v2
	v_exp_f32_e32 v2, v2
	v_rcp_f32_e32 v0, v0
	ds_read_b32 v3, v54 offset:13000
	v_and_b32_e32 v18, 1, v28
	v_fma_f32 v1, -v2, v2, 1.0
	v_max_f32_e32 v1, 0, v1
	v_sqrt_f32_e32 v1, v1
	v_or_b32_e32 v4, 2, v15
	v_or_b32_e32 v6, 3, v15
	v_cmp_eq_u32_e32 vcc, 0, v18
	v_mul_f32_e32 v0, v0, v1
	v_or_b32_e32 v1, 0x3300, v64
	s_waitcnt lgkmcnt(0)
	v_mul_f32_e32 v0, v0, v3
	v_add_u32_e32 v3, 0, v1
	ds_write_b32 v3, v2 offset:62720
	v_add_u32_e32 v1, s0, v1
	v_or_b32_e32 v2, 1, v15
	ds_write_b32 v1, v0
	v_sub_u32_e32 v0, 63, v15
	v_sub_u32_e32 v3, 63, v2
	v_sub_u32_e32 v5, 63, v4
	v_sub_u32_e32 v7, 63, v6
	v_cndmask_b32_e32 v0, v0, v15, vcc
	v_cndmask_b32_e32 v2, v3, v2, vcc
	v_cndmask_b32_e32 v4, v5, v4, vcc
	v_cndmask_b32_e32 v6, v7, v6, vcc
	v_lshl_or_b32 v19, v18, 12, v31
	v_lshlrev_b32_e32 v0, 6, v0
	v_lshlrev_b32_e32 v2, 6, v2
	v_lshlrev_b32_e32 v4, 6, v4
	v_lshlrev_b32_e32 v6, 6, v6
	v_add_lshl_u32 v0, v0, v19, 2
	v_add_lshl_u32 v2, v2, v19, 2
	v_add_lshl_u32 v4, v4, v19, 2
	v_add_lshl_u32 v6, v6, v19, 2
	v_add_u32_e32 v1, 0, v0
	v_add_u32_e32 v0, s0, v0
	v_add_u32_e32 v3, 0, v2
	v_add_u32_e32 v2, s0, v2
	v_add_u32_e32 v5, 0, v4
	v_add_u32_e32 v7, 0, v6
	s_waitcnt lgkmcnt(0)
	s_barrier
; __device__ void rg_tile(unsigned char* lds, const Params& p, int l, int b, int ck, int hh, bool outmode) {
;     ...
;   {
;     float* SEG = XR;
;     const int seg = tid >> 7, d = (tid >> 6) & 1, j = tid & 63;
;     const int ch = hh * 64 + j;
;     const size_t ci = ((size_t)(b * 36 + ck) * 2 + d) * 256 + ch;
;     float H = 0.f, Ap = 1.f;
; #pragma unroll
;     for (int q = 0; q < 16; ++q) {
;       const int pos = seg * 16 + q;
;       const int tt = d == 0 ? pos : 63 - pos;
;       const float a = AA[(d * 64 + tt) * 64 + j];
;       H = a * H + BQ[(d * 64 + tt) * 64 + j];
;       Ap *= a;
;     }
;     SEG[((seg * 2 + d) * 64 + j) * 2 + 0] = Ap;
;     SEG[((seg * 2 + d) * 64 + j) * 2 + 1] = H;
;     __syncthreads();
;     if (!outmode) {
;       if (seg == 0) {
;         float Ht = 0.f, At = 1.f;
; #pragma unroll
;         for (int sgi = 0; sgi < 4; ++sgi) {
;           const float as = SEG[((sgi * 2 + d) * 64 + j) * 2 + 0], hs = SEG[((sgi * 2 + d) * 64 + j) * 2 + 1];
;           Ht = as * Ht + hs;
;           At *= as;
;         }
;         agg[ci * 2 + 0] = At;
;         agg[ci * 2 + 1] = Ht;
;       }
	v_add_u32_e32 v4, s0, v4
	v_add_u32_e32 v6, s0, v6
	ds_read_b32 v1, v1 offset:62720
	ds_read_b32 v8, v0
	ds_read_b32 v3, v3 offset:62720
	ds_read_b32 v9, v2
	ds_read_b32 v0, v5 offset:62720
	ds_read_b32 v5, v4
	ds_read_b32 v2, v7 offset:62720
	ds_read_b32 v7, v6
	s_waitcnt lgkmcnt(6)
	v_fmac_f32_e32 v8, 0, v1
	v_or_b32_e32 v6, 5, v15
	s_waitcnt lgkmcnt(4)
	v_fmac_f32_e32 v9, v8, v3
	v_sub_u32_e32 v8, 63, v6
	v_cndmask_b32_e32 v6, v8, v6, vcc
	v_lshlrev_b32_e32 v6, 6, v6
	v_add_lshl_u32 v6, v6, v19, 2
	s_waitcnt lgkmcnt(2)
	v_fmac_f32_e32 v5, v9, v0
	v_add_u32_e32 v8, 0, v6
	v_add_u32_e32 v9, s0, v6
	v_or_b32_e32 v6, 6, v15
	v_sub_u32_e32 v10, 63, v6
	v_cndmask_b32_e32 v6, v10, v6, vcc
	v_lshlrev_b32_e32 v6, 6, v6
	v_add_lshl_u32 v6, v6, v19, 2
	v_mul_f32_e32 v4, v1, v3
	v_or_b32_e32 v1, 4, v15
	v_add_u32_e32 v10, 0, v6
	v_add_u32_e32 v11, s0, v6
	v_or_b32_e32 v6, 7, v15
	v_sub_u32_e32 v3, 63, v1
	v_sub_u32_e32 v12, 63, v6
	v_cndmask_b32_e32 v1, v3, v1, vcc
	v_cndmask_b32_e32 v6, v12, v6, vcc
	v_lshlrev_b32_e32 v1, 6, v1
	v_lshlrev_b32_e32 v6, 6, v6
	v_add_lshl_u32 v1, v1, v19, 2
	v_add_lshl_u32 v6, v6, v19, 2
	v_add_u32_e32 v3, 0, v1
	v_add_u32_e32 v1, s0, v1
	v_add_u32_e32 v12, 0, v6
	v_add_u32_e32 v13, s0, v6
	ds_read_b32 v6, v3 offset:62720
	ds_read_b32 v1, v1
	ds_read_b32 v8, v8 offset:62720
	ds_read_b32 v3, v9
	ds_read_b32 v10, v10 offset:62720
	ds_read_b32 v9, v11
	ds_read_b32 v12, v12 offset:62720
	ds_read_b32 v16, v13
	s_waitcnt lgkmcnt(8)
	v_fmac_f32_e32 v7, v5, v2
	v_or_b32_e32 v5, 9, v15
	s_waitcnt lgkmcnt(6)
	v_fmac_f32_e32 v1, v7, v6
	v_sub_u32_e32 v7, 63, v5
	v_cndmask_b32_e32 v5, v7, v5, vcc
	s_waitcnt lgkmcnt(4)
	v_fmac_f32_e32 v3, v1, v8
	v_lshlrev_b32_e32 v5, 6, v5
	s_waitcnt lgkmcnt(2)
	v_fmac_f32_e32 v9, v3, v10
	v_add_lshl_u32 v5, v5, v19, 2
	s_waitcnt lgkmcnt(0)
	v_fmac_f32_e32 v16, v9, v12
	v_add_u32_e32 v7, 0, v5
	v_add_u32_e32 v9, s0, v5
	v_or_b32_e32 v5, 10, v15
	v_sub_u32_e32 v11, 63, v5
	v_cndmask_b32_e32 v5, v11, v5, vcc
	v_lshlrev_b32_e32 v5, 6, v5
	v_or_b32_e32 v1, 8, v15
	v_add_lshl_u32 v5, v5, v19, 2
	v_sub_u32_e32 v3, 63, v1
	v_add_u32_e32 v11, 0, v5
	v_add_u32_e32 v13, s0, v5
	v_or_b32_e32 v5, 11, v15
	v_cndmask_b32_e32 v1, v3, v1, vcc
	v_sub_u32_e32 v14, 63, v5
	v_lshlrev_b32_e32 v1, 6, v1
	v_cndmask_b32_e32 v5, v14, v5, vcc
	v_add_lshl_u32 v1, v1, v19, 2
	v_lshlrev_b32_e32 v5, 6, v5
	v_add_u32_e32 v3, 0, v1
	v_add_u32_e32 v1, s0, v1
	v_add_lshl_u32 v5, v5, v19, 2
	v_add_u32_e32 v17, 0, v5
	v_add_u32_e32 v20, s0, v5
	ds_read_b32 v14, v3 offset:62720
	ds_read_b32 v5, v1
	ds_read_b32 v1, v7 offset:62720
	ds_read_b32 v3, v9
	ds_read_b32 v7, v11 offset:62720
	ds_read_b32 v9, v13
	ds_read_b32 v11, v17 offset:62720
	ds_read_b32 v13, v20
	s_waitcnt lgkmcnt(6)
	v_fmac_f32_e32 v5, v16, v14
	v_mul_f32_e32 v16, v4, v0
	v_mul_f32_e32 v16, v16, v2
	s_waitcnt lgkmcnt(4)
	v_pk_fma_f32 v[2:3], v[4:5], v[0:1], v[2:3]
	v_or_b32_e32 v0, 12, v15
	v_mov_b32_e32 v17, v3
	s_waitcnt lgkmcnt(3)
	v_pk_mul_f32 v[2:3], v[16:17], v[6:7]
	s_waitcnt lgkmcnt(2)
	v_pk_fma_f32 v[4:5], v[16:17], v[6:7], v[8:9]
	v_pk_mul_f32 v[2:3], v[2:3], v[8:9]
	v_or_b32_e32 v8, 13, v15
	v_sub_u32_e32 v9, 63, v8
	v_cndmask_b32_e32 v8, v9, v8, vcc
	v_or_b32_e32 v9, 14, v15
	v_sub_u32_e32 v17, 63, v9
	v_cndmask_b32_e32 v9, v17, v9, vcc
	v_lshlrev_b32_e32 v9, 6, v9
	v_add_lshl_u32 v9, v9, v19, 2
	v_sub_u32_e32 v6, 63, v0
	v_add_u32_e32 v20, 0, v9
	v_add_u32_e32 v22, s0, v9
	v_or_b32_e32 v9, 15, v15
	v_cndmask_b32_e32 v0, v6, v0, vcc
	v_sub_u32_e32 v15, 63, v9
	v_lshlrev_b32_e32 v0, 6, v0
	v_cndmask_b32_e32 v9, v15, v9, vcc
	v_add_lshl_u32 v0, v0, v19, 2
	v_lshlrev_b32_e32 v8, 6, v8
	v_lshlrev_b32_e32 v9, 6, v9
	v_mov_b32_e32 v4, v2
	v_add_u32_e32 v6, 0, v0
	v_add_u32_e32 v0, s0, v0
	v_add_lshl_u32 v8, v8, v19, 2
	v_add_lshl_u32 v9, v9, v19, 2
	s_waitcnt lgkmcnt(1)
	v_pk_mul_f32 v[2:3], v[2:3], v[10:11]
	v_add_u32_e32 v16, 0, v8
	v_add_u32_e32 v8, s0, v8
	v_add_u32_e32 v24, 0, v9
	v_add_u32_e32 v26, s0, v9
	ds_read_b32 v15, v6 offset:62720
	ds_read_b32 v9, v0
	ds_read_b32 v17, v16 offset:62720
	ds_read_b32 v19, v8
	ds_read_b32 v21, v20 offset:62720
	ds_read_b32 v23, v22
	ds_read_b32 v25, v24 offset:62720
	ds_read_b32 v27, v26
	v_and_b32_e32 v0, 0x1fffff80, v29
	v_lshlrev_b32_e32 v6, 6, v18
	s_waitcnt lgkmcnt(8)
	v_pk_mul_f32 v[2:3], v[2:3], v[12:13]
	v_pk_fma_f32 v[4:5], v[4:5], v[10:11], v[12:13]
	v_or3_b32 v0, v6, v0, v31
	v_mov_b32_e32 v3, v5
	v_lshl_add_u32 v6, v0, 3, 0
	s_waitcnt lgkmcnt(7)
	v_pk_mul_f32 v[4:5], v[2:3], v[14:15]
	v_mov_b32_e32 v0, v1
	v_mov_b32_e32 v8, v1
	v_pk_mul_f32 v[0:1], v[4:5], v[0:1]
	s_waitcnt lgkmcnt(6)
	v_pk_fma_f32 v[2:3], v[2:3], v[14:15], v[8:9]
	v_mov_b32_e32 v4, v7
	v_mov_b32_e32 v2, v0
	v_mov_b32_e32 v16, v7
	v_pk_mul_f32 v[0:1], v[0:1], v[4:5]
	v_mov_b32_e32 v4, v11
	v_mov_b32_e32 v18, v11
	v_pk_mul_f32 v[0:1], v[0:1], v[4:5]
	s_waitcnt lgkmcnt(4)
	v_pk_fma_f32 v[2:3], v[2:3], v[16:17], v[18:19]
	v_mov_b32_e32 v20, v15
	v_mov_b32_e32 v1, v3
	s_waitcnt lgkmcnt(3)
	v_pk_mul_f32 v[2:3], v[0:1], v[20:21]
	v_mov_b32_e32 v4, v17
	v_mov_b32_e32 v22, v17
	v_pk_mul_f32 v[2:3], v[2:3], v[4:5]
	s_waitcnt lgkmcnt(2)
	v_pk_fma_f32 v[0:1], v[0:1], v[20:21], v[22:23]
	v_mov_b32_e32 v4, v21
	v_mov_b32_e32 v0, v2
	v_mov_b32_e32 v24, v21
	v_pk_mul_f32 v[2:3], v[2:3], v[4:5]
	s_waitcnt lgkmcnt(1)
	v_mov_b32_e32 v4, v25
	v_mov_b32_e32 v26, v25
	v_pk_mul_f32 v[2:3], v[2:3], v[4:5]
	s_waitcnt lgkmcnt(0)
	v_pk_fma_f32 v[0:1], v[0:1], v[24:25], v[26:27]
	v_cmp_gt_u32_e32 vcc, s91, v29
	v_mov_b32_e32 v3, v1
	ds_write_b64 v6, v[2:3]
	s_waitcnt lgkmcnt(0)
	s_barrier
	s_and_saveexec_b64 s[0:1], vcc
	s_cbranch_execz .LBB0_329
	v_lshlrev_b32_e32 v0, 3, v29
	v_add_u32_e32 v4, 0, v0
	ds_read2st64_b64 v[0:3], v4 offset1:2
	ds_read2st64_b64 v[4:7], v4 offset0:4 offset1:6
	s_mul_i32 s3, s3, 36
	s_add_i32 s3, s3, s2
	s_lshl_b32 s2, s3, 9
	s_waitcnt lgkmcnt(1)
	v_fma_f32 v1, 0, v0, v1
	v_fmac_f32_e32 v3, v1, v2
	v_lshlrev_b32_e32 v8, 8, v28
	v_mul_f32_e32 v0, v0, v2
	s_waitcnt lgkmcnt(0)
	v_fma_f32 v1, v3, v4, v5
	v_mov_b32_e32 v5, v6
	v_or3_b32 v192, v8, s2, v30
	v_readlane_b32 s2, v251, 56
	v_pk_mul_f32 v[8:9], v[0:1], v[4:5]
	v_readlane_b32 s3, v251, 57
	v_pk_mul_f32 v[8:9], v[8:9], v[6:7]
	v_pk_fma_f32 v[0:1], v[0:1], v[4:5], v[6:7]
	v_lshl_add_u64 v[2:3], v[192:193], 3, s[2:3]
	v_mov_b32_e32 v9, v1
	global_store_dwordx2 v[2:3], v[8:9], off

; __device__ __forceinline__ void ml_prep_load(const float* G, int b, int n, int h, int tid, float* g4) {
;   const bool isctx = n < 2;
;   const int p0 = isctx ? n * 128 : (n - 2) * 128;
;   const float* g = G + (size_t)ml_row_pos(b, isctx, p0 + (tid & 127)) * 16;
;   g4[0] = g[0 + h]; g4[1] = g[4 + h]; g4[2] = g[8 + h]; g4[3] = g[12 + h];
; }
; __device__ void ml_local_tile(unsigned char* lds, const Params& p, int l, int b, int h, int n) {
;     ...
;   uint4 ku[4][4], vu[4];
;   {
;     const int s = tid & 127, ec0 = tid >> 7;
;     const int row = ml_row_pos(b, isctx, p0 + s);
; #pragma unroll
;     for (int i = 0; i < 4; ++i) {
;       const int ec = ec0 + 4 * i;
;       ml_conv8_load(z, 768 + 512 + h * 128 + ec * 8, b, isctx, L, p0 + s, ku[i]);
;       vu[i] = *(const uint4*)(z + (size_t)row * ZS + 768 + 1024 + h * 128 + ec * 8);
;     }
.LBB0_336:
	v_ashrrev_i32_e32 v1, 31, v0
	v_readlane_b32 s2, v251, 0
	s_and_b32 s25, s21, 3
	v_lshlrev_b64 v[0:1], 6, v[0:1]
	v_readlane_b32 s3, v251, 1
	s_lshl_b32 s96, s25, 2
	s_and_b64 vcc, exec, s[0:1]
	v_lshl_add_u64 v[0:1], s[2:3], 0, v[0:1]
	v_lshl_add_u64 v[0:1], v[0:1], 0, s[96:97]
	s_movk_i32 s46, 0x80
	v_cmp_gt_u32_e64 s[44:45], s46, v88
	s_and_saveexec_b64 s[46:47], s[44:45]
	global_load_dword v89, v[0:1], off
	global_load_dword v90, v[0:1], off offset:16
	global_load_dword v80, v[0:1], off offset:32
	global_load_dword v81, v[0:1], off offset:48
	s_mov_b64 exec, s[46:47]
	v_lshrrev_b32_e32 v108, 2, v88
	v_and_b32_e32 v109, 3, v88
	v_or_b32_e32 v92, s4, v108
	v_lshlrev_b32_e32 v4, 6, v92
	v_and_b32_e32 v4, 0x7c0, v4
	v_ashrrev_i32_e32 v3, 5, v92
	s_mov_b64 s[2:3], -1
	s_cbranch_vccz .LBB0_338
	s_lshl_b32 s1, s5, 8
	s_lshl_b32 s0, s5, 11
	s_addk_i32 s1, 0x4000
	v_add3_u32 v2, v3, s0, v4
	s_mov_b64 s[2:3], 0
	v_mov_b32_e32 v0, s1
	v_mov_b32_e32 v1, s0

; __device__ __forceinline__ float bf2f(bf16_t h) { return __uint_as_float(((unsigned)h) << 16); }
; __device__ void rg_tile(unsigned char* lds, const Params& p, int l, int b, int ck, int hh, bool outmode) {
;     ...
;   const bool isctx = ck < 4;
;   const int L = isctx ? 256 : 2048;
;   const int t0 = isctx ? ck * 64 : (ck - 4) * 64;
;   const int rowbase = isctx ? (NLAT + b * 256) : (b * 2048);
;   float car_pre = 0.f, gp_pre[8];
;   {
;     const int d_ = (tid >> 6) & 1, j_ = tid & 63;
;     if (outmode) {
;       car_pre = car[((size_t)(b * 36 + ck) * 2 + d_) * 256 + hh * 64 + j_];
; #pragma unroll
;       for (int q = 0; q < 8; ++q) gp_pre[q] = bf2f(z[(size_t)(rowbase + t0 + w * 8 + q) * ZS + 2816 + 256 + hh * 64 + lane]);
;     } else {
; #pragma unroll
;       for (int q = 0; q < 8; ++q) gp_pre[q] = 0.f;
;     }
;   }
;   const int chm_ = hh * 64 + (w & 3) * 16 + lr, dm_ = w >> 2;
;   const float br = p.in[22][(size_t)l * 1024 + (dm_ * 2 + 0) * 256 + chm_];
;   const float bi = p.in[22][(size_t)l * 1024 + (dm_ * 2 + 1) * 256 + chm_];
;   const float lam_ = p.in[23][(size_t)l * 512 + dm_ * 256 + chm_];
;   {
;     const int i = tid & 63, tq = tid >> 6;
;     const int ch = hh * 64 + i;
;     const float* wc = p.in[20] + (size_t)l * 4 * 256 + ch;
;     const float w0 = wc[0], w1 = wc[256], w2 = wc[512], w3 = wc[768];
; #pragma unroll
;     for (int ii = 0; ii < 8; ++ii) {
;       const int tt = tq * 8 + ii;
;       const int tp = t0 + tt;
;       const int tm1 = tp - 1 >= 0 ? tp - 1 : 0, tp1 = tp + 1 < L ? tp + 1 : L - 1, tp2 = tp + 2 < L ? tp + 2 : L - 1;
;       const float z0 = bf2f(z[(size_t)(rowbase + tm1) * ZS + 2816 + ch]);
;       const float z1 = bf2f(z[(size_t)(rowbase + tp) * ZS + 2816 + ch]);
;       const float z2 = bf2f(z[(size_t)(rowbase + tp1) * ZS + 2816 + ch]);
;       const float z3 = bf2f(z[(size_t)(rowbase + tp2) * ZS + 2816 + ch]);
; __global__ void __launch_bounds__(512) fwd_kernel(Params p) {
;     ...
;           const int tile = item - n_ml;
;           const int hh = tile & 3, ck = cfirst + (tile >> 2) % ccnt, b = tile / (4 * ccnt);
;           rg_tile(lds, p, l, b, ck, hh, true);
.LBB0_708:
	s_and_b64 vcc, exec, s[0:1]
	s_cbranch_vccz .LBB0_812
	s_sub_i32 s0, s13, s30
	s_ashr_i32 s2, s0, 2
	s_abs_i32 s2, s2
	v_readlane_b32 s3, v254, 14
	s_mul_hi_u32 s3, s2, s3
	v_readlane_b32 s4, v254, 11
	s_mul_i32 s3, s3, s4
	s_sub_i32 s2, s2, s3
	s_and_b32 s1, s13, 3
	s_sub_i32 s3, s2, s4
	s_cmp_ge_u32 s2, s4
	s_cselect_b32 s2, s3, s2
	s_sub_i32 s3, s2, s4
	s_cmp_ge_u32 s2, s4
	s_cselect_b32 s2, s3, s2
	s_ashr_i32 s3, s0, 31
	s_xor_b32 s2, s2, s3
	s_sub_i32 s2, s2, s3
	v_readlane_b32 s4, v254, 22
	s_add_i32 s4, s2, s4
	s_abs_i32 s0, s0
	v_readlane_b32 s2, v254, 16
	s_mul_hi_u32 s2, s0, s2
	v_readlane_b32 s7, v254, 15
	s_mul_i32 s5, s2, s7
	s_sub_i32 s0, s0, s5
	s_add_i32 s5, s2, 1
	s_sub_i32 s6, s0, s7
	s_cmp_ge_u32 s0, s7
	s_cselect_b32 s2, s5, s2
	s_cselect_b32 s0, s6, s0
	s_add_i32 s5, s2, 1
	s_cmp_ge_u32 s0, s7
	s_cselect_b32 s0, s5, s2
	s_xor_b32 s0, s0, s3
	s_sub_i32 s5, s0, s3
	s_lshl_b32 s2, s4, 6
	s_lshl_b32 s0, s5, 8
	s_add_i32 s3, s2, 0xffffff00
	s_add_i32 s6, s0, 0x4000
	s_lshl_b32 s7, s5, 11
	s_cmp_lt_i32 s4, 4
	s_movk_i32 s0, 0x800
	s_mul_i32 s5, s5, 36
	s_cselect_b32 s0, 0x100, s0
	s_cselect_b32 s3, s2, s3
	s_cselect_b32 s2, s6, s7
	s_add_i32 s4, s5, s4
	v_mov_b32_e32 v52, v195
	v_readfirstlane_b32 s44, v195
	s_mov_b32 s47, s0
	s_mov_b32 s48, s2
	s_mov_b32 s49, s3
	s_lshl_b32 s50, s1, 7
	s_lshr_b32 s44, s44, 6
	s_lshl_b32 s45, s44, 3
	s_add_i32 s45, s45, s49
	s_add_i32 s46, s47, -1
	s_addk_i32 s50, 0x1600
	v_and_b32_e32 v185, 63, v195
	v_lshl_add_u32 v180, v185, 1, s50
	v_readlane_b32 s52, v254, 3
	v_readlane_b32 s53, v254, 4
	s_lshl_b32 s51, s1, 8
	v_lshl_add_u32 v181, v185, 2, s51
	s_nop 2
	global_load_dword v165, v181, s[52:53]
	s_nop 1
	global_load_dword v166, v181, s[52:53] offset:1024
	s_nop 0
	global_load_dword v167, v181, s[52:53] offset:2048
	global_load_dword v168, v181, s[52:53] offset:3072
	s_add_i32 s54, s45, s48
	s_mul_i32 s54, s54, 0x1a00
	s_and_b32 s56, s13, 3
	v_bfe_u32 v208, v195, 4, 2
	v_and_b32_e32 v209, 15, v195
	v_mul_u32_u24_e32 v210, 0x1a00, v208
	v_lshl_add_u32 v210, v209, 3, v210
	s_add_i32 s57, s54, s50
	s_addk_i32 s57, 0x200
	v_add_u32_e32 v210, s57, v210
	v_readlane_b32 s58, v254, 9
	v_readlane_b32 s59, v254, 10
	global_load_dwordx2 v[204:205], v210, s[88:89]
	v_add_u32_e32 v210, 0x6800, v210
	global_load_dwordx2 v[206:207], v210, s[88:89]
	s_lshl_b32 s57, s56, 8
	s_addk_i32 s57, 0xc00
	v_lshl_add_u32 v211, v209, 4, s57
	global_load_dwordx4 v[200:203], v211, s[58:59]
	v_add_u32_e32 v181, s54, v180
	s_add_i32 s55, s45, -1
	s_max_i32 s55, s55, 0
	s_add_i32 s55, s55, s48
	s_mul_i32 s55, s55, 0x1a00
	v_add_u32_e32 v184, s55, v180
	global_load_ushort v154, v184, s[88:89]
	global_load_ushort v155, v181, s[88:89]
	v_add_u32_e32 v181, 0x1a00, v181
	global_load_ushort v156, v181, s[88:89]
	v_add_u32_e32 v181, 0x1a00, v181
	global_load_ushort v157, v181, s[88:89]
	v_add_u32_e32 v181, 0x1a00, v181
	global_load_ushort v158, v181, s[88:89]
	v_add_u32_e32 v181, 0x1a00, v181
	global_load_ushort v159, v181, s[88:89]
	v_add_u32_e32 v181, 0x1a00, v181
	global_load_ushort v160, v181, s[88:89]
	v_add_u32_e32 v181, 0x1a00, v181
	global_load_ushort v161, v181, s[88:89]
	v_add_u32_e32 v181, 0x1a00, v181
	global_load_ushort v162, v181, s[88:89]
	s_add_i32 s55, s45, 8
	s_min_i32 s55, s55, s46
	s_add_i32 s55, s55, s48
	s_mul_i32 s55, s55, 0x1a00
	v_add_u32_e32 v184, s55, v180
	global_load_ushort v163, v184, s[88:89]
	s_add_i32 s55, s45, 9
	s_min_i32 s55, s55, s46
	s_add_i32 s55, s55, s48
	s_mul_i32 s55, s55, 0x1a00
	v_add_u32_e32 v184, s55, v180
	global_load_ushort v164, v184, s[88:89]
	s_mul_i32 s55, s44, 0x820
	v_lshl_add_u32 v182, v185, 2, s55
	s_mul_i32 s55, s44, 0x480
	v_lshl_add_u32 v183, v185, 1, s55
	s_ashr_i32 s5, s4, 31
	s_lshl_b32 s7, s1, 6
	v_ashrrev_i32_e32 v47, 6, v52
	s_lshl_b64 s[4:5], s[4:5], 11
	v_readlane_b32 s8, v252, 11
	v_and_b32_e32 v48, 1, v47
	v_readlane_b32 s9, v252, 12
	s_add_u32 s4, s8, s4
	s_addc_u32 s5, s9, s5
	v_lshlrev_b32_e32 v192, 10, v48
	v_and_b32_e32 v29, 63, v52
	v_lshl_add_u64 v[0:1], s[4:5], 0, v[192:193]
	s_lshl_b32 s96, s1, 8
	v_lshl_add_u64 v[0:1], v[0:1], 0, s[96:97]
	v_lshlrev_b32_e32 v192, 2, v29
	s_add_i32 s4, s3, s2
	v_lshlrev_b32_e32 v12, 3, v47
	v_lshl_add_u64 v[2:3], v[0:1], 0, v[192:193]
	v_add_u32_e32 v28, s4, v12
	v_mov_b64_e32 v[0:1], s[88:89]
	s_lshl_b32 s96, s1, 7
	s_movk_i32 s10, 0x1000
	global_load_dword v51, v[2:3], off
	s_add_i32 s6, s2, -1
	v_or_b32_e32 v7, s7, v29
	v_lshlrev_b32_e32 v32, 1, v7
	v_mov_b32_e32 v33, v193
	v_lshlrev_b32_e32 v39, 2, v7
	s_add_i32 s5, s0, -1
	v_and_b32_e32 v6, 15, v52
	v_lshlrev_b32_e32 v2, 4, v47
	v_ashrrev_i32_e32 v56, 8, v52
	v_and_or_b32 v55, v2, 48, v6
	v_lshlrev_b32_e32 v2, 9, v56
	v_readlane_b32 s8, v254, 12
	v_lshl_or_b32 v7, v56, 1, 1
	v_or_b32_e32 v4, s7, v55
	v_ashrrev_i32_e32 v3, 31, v2
	v_readlane_b32 s9, v254, 13
	v_lshlrev_b32_e32 v16, 8, v7
	v_lshlrev_b32_e32 v4, 2, v4
	v_lshl_add_u64 v[2:3], v[2:3], 2, s[8:9]
	v_mov_b32_e32 v5, v193
	v_ashrrev_i32_e32 v17, 31, v16
	v_lshl_add_u64 v[2:3], v[2:3], 0, v[4:5]
	v_lshl_add_u64 v[16:17], v[16:17], 2, s[8:9]
	v_lshl_add_u64 v[16:17], v[16:17], 0, v[4:5]
	global_load_dword v54, v[2:3], off
	global_load_dword v53, v[16:17], off
	v_and_b32_e32 v2, 0xffffff00, v52
	v_readlane_b32 s8, v254, 1
	v_ashrrev_i32_e32 v3, 31, v2
	v_readlane_b32 s9, v254, 2
	v_or_b32_e32 v37, 1, v12
	v_add_u32_e32 v30, 0, v192
	v_lshl_add_u64 v[2:3], v[2:3], 2, s[8:9]
	v_lshl_add_u64 v[2:3], v[2:3], 0, v[4:5]
	global_load_dword v16, v[2:3], off
	v_or_b32_e32 v38, 2, v12
	v_or_b32_e32 v40, 3, v12
	v_or_b32_e32 v43, 4, v12
	s_movk_i32 s12, 0x104
	s_movk_i32 s11, 0x90
	v_or_b32_e32 v44, 5, v12
; __device__ __forceinline__ bf16_t f2bf(float f) { return (bf16_t)(pack2(f, 0.f) & 0xffffu); }
; __device__ __forceinline__ float bf2f(bf16_t h) { return __uint_as_float(((unsigned)h) << 16); }
; __device__ void rg_tile(unsigned char* lds, const Params& p, int l, int b, int ck, int hh, bool outmode) {
;     ...
;     const int i = tid & 63, tq = tid >> 6;
;     const int ch = hh * 64 + i;
;     const float* wc = p.in[20] + (size_t)l * 4 * 256 + ch;
;     const float w0 = wc[0], w1 = wc[256], w2 = wc[512], w3 = wc[768];
; #pragma unroll
;     for (int ii = 0; ii < 8; ++ii) {
;       const int tt = tq * 8 + ii;
;       const int tp = t0 + tt;
;       const int tm1 = tp - 1 >= 0 ? tp - 1 : 0, tp1 = tp + 1 < L ? tp + 1 : L - 1, tp2 = tp + 2 < L ? tp + 2 : L - 1;
;       const float z0 = bf2f(z[(size_t)(rowbase + tm1) * ZS + 2816 + ch]);
;       const float z1 = bf2f(z[(size_t)(rowbase + tp) * ZS + 2816 + ch]);
;       const float z2 = bf2f(z[(size_t)(rowbase + tp1) * ZS + 2816 + ch]);
;       const float z3 = bf2f(z[(size_t)(rowbase + tp2) * ZS + 2816 + ch]);
;       float xr = w1 * z1;
;       xr += (tp - 1 >= 0 ? w0 : 0.f) * z0;
;       xr += (tp + 1 < L ? w2 : 0.f) * z2;
;       xr += (tp + 2 < L ? w3 : 0.f) * z3;
;       XR[tt * 65 + i] = xr;
;       XB[tt * 72 + i] = f2bf(xr);
;     }
;     const bf16_t* rgw = (const bf16_t*)(p.ws + OFF_RGW);
; #pragma unroll
;     for (int q = 0; q < 4; ++q) {
;       const int id = tid + 512 * q;
;       const int row = id >> 3, kc = id & 7;
;       *(uint4*)(WT + row * 72 + kc * 8) = *(const uint4*)(rgw + ((size_t)((l * 4 + (row >> 6)) * 4 + hh)) * 4096 + (row & 63) * 64 + kc * 8);
;     }
;   }
;   __syncthreads();
	v_or_b32_e32 v45, 6, v12
	v_add_u32_e32 v68, s3, v45
	v_add_u32_e32 v69, 2, v68
	v_min_i32_e32 v26, s5, v69
	v_or_b32_e32 v46, 7, v12
	v_add_u32_e32 v13, s2, v26
	v_add_u32_e32 v70, s3, v46
	v_mad_i64_i32 v[26:27], s[8:9], v13, s92, v[0:1]
	v_max_i32_e32 v12, 1, v70
	v_add_u32_e32 v12, s6, v12
	v_mad_u64_u32 v[12:13], s[6:7], v12, s92, v[0:1]
	v_lshl_add_u64 v[12:13], v[12:13], 0, v[32:33]
	v_add_u32_e32 v58, s2, v70
	v_add_co_u32_e32 v12, vcc, s10, v12
	v_mad_i64_i32 v[58:59], s[6:7], v58, s92, v[0:1]
	s_nop 0
	v_addc_co_u32_e32 v13, vcc, 0, v13, vcc
	v_ashrrev_i32_e32 v80, 3, v52
	global_load_ushort v78, v[12:13], off offset:1536
	v_readlane_b32 s2, v254, 5
	v_lshlrev_b32_e32 v12, 4, v52
	v_ashrrev_i32_e32 v33, 7, v52
	s_or_b32 s1, s1, s2
	v_and_b32_e32 v26, 0x70, v12
	v_and_b32_e32 v12, -4, v33
	v_add_u32_e32 v12, s1, v12
	v_ashrrev_i32_e32 v13, 31, v12
	v_readlane_b32 s2, v251, 22
	v_lshlrev_b64 v[12:13], 13, v[12:13]
	v_readlane_b32 s3, v251, 23
	v_lshlrev_b32_e32 v14, 7, v80
	v_and_b32_e32 v14, 0x1f80, v14
	v_lshl_add_u64 v[12:13], s[2:3], 0, v[12:13]
	v_mov_b32_e32 v15, v193
	v_lshl_add_u64 v[12:13], v[12:13], 0, v[14:15]
	v_mov_b32_e32 v27, v193
	v_lshl_add_u64 v[12:13], v[12:13], 0, v[26:27]
	global_load_dwordx4 v[12:15], v[12:13], off
	v_add_u32_e32 v0, 0x200, v52
	v_ashrrev_i32_e32 v82, 3, v0
	v_ashrrev_i32_e32 v0, 7, v0
	v_and_b32_e32 v0, -4, v0
	v_add_u32_e32 v0, s1, v0
	v_ashrrev_i32_e32 v1, 31, v0
	v_lshlrev_b64 v[0:1], 13, v[0:1]
	v_lshlrev_b32_e32 v18, 7, v82
	v_lshl_add_u64 v[0:1], s[2:3], 0, v[0:1]
	v_and_b32_e32 v18, 0x1f80, v18
	v_mov_b32_e32 v19, v193
	v_lshl_add_u64 v[0:1], v[0:1], 0, v[18:19]
	v_add_u32_e32 v18, 0x400, v52
	v_ashrrev_i32_e32 v83, 3, v18
	v_ashrrev_i32_e32 v18, 7, v18
	v_and_b32_e32 v18, -4, v18
	v_add_u32_e32 v18, s1, v18
	v_ashrrev_i32_e32 v19, 31, v18
	v_lshlrev_b64 v[18:19], 13, v[18:19]
	v_lshlrev_b32_e32 v20, 7, v83
	v_lshl_add_u64 v[18:19], s[2:3], 0, v[18:19]
	v_and_b32_e32 v20, 0x1f80, v20
	v_mov_b32_e32 v21, v193
	v_lshl_add_u64 v[18:19], v[18:19], 0, v[20:21]
	v_lshl_add_u64 v[0:1], v[0:1], 0, v[26:27]
	v_lshl_add_u64 v[22:23], v[18:19], 0, v[26:27]
	global_load_dwordx4 v[18:21], v[0:1], off
	global_load_dwordx4 v[22:25], v[22:23], off
	v_add_u32_e32 v0, 0x600, v52
	v_ashrrev_i32_e32 v84, 3, v0
	v_ashrrev_i32_e32 v0, 7, v0
	v_and_b32_e32 v0, -4, v0
	v_add_u32_e32 v0, s1, v0
	v_ashrrev_i32_e32 v1, 31, v0
	v_lshlrev_b64 v[0:1], 13, v[0:1]
	v_lshlrev_b32_e32 v58, 7, v84
	v_lshl_add_u64 v[0:1], s[2:3], 0, v[0:1]
	v_and_b32_e32 v58, 0x1f80, v58
	v_mov_b32_e32 v59, v193
	v_lshl_add_u64 v[0:1], v[0:1], 0, v[58:59]
	v_lshl_add_u64 v[0:1], v[0:1], 0, v[26:27]
	global_load_dwordx4 v[58:61], v[0:1], off
	s_waitcnt vmcnt(0)
	v_lshlrev_b32_e32 v1, 16, v78
	v_add_u32_e32 v0, 0, v26
	v_mad_u64_u32 v[2:3], s[0:1], v80, s11, v[0:1]
	ds_write_b128 v2, v[12:15] offset:25856
	v_mad_u64_u32 v[2:3], s[0:1], v82, s11, v[0:1]
	ds_write_b128 v2, v[18:21] offset:25856
	v_mad_u64_u32 v[2:3], s[0:1], v83, s11, v[0:1]
	v_mad_u64_u32 v[0:1], s[0:1], v84, s11, v[0:1]
	ds_write_b128 v2, v[22:25] offset:25856
	ds_write_b128 v0, v[58:61] offset:25856
	v_and_b32_e32 v0, 48, v52
	v_add_u32_e32 v0, 0, v0
	v_mad_u32_u24 v17, v6, s11, v0
	s_waitcnt vmcnt(0)
	v_lshlrev_b32_e32 v154, 16, v154
	v_lshlrev_b32_e32 v155, 16, v155
	v_lshlrev_b32_e32 v156, 16, v156
	v_lshlrev_b32_e32 v157, 16, v157
	v_lshlrev_b32_e32 v158, 16, v158
	v_lshlrev_b32_e32 v159, 16, v159
	v_lshlrev_b32_e32 v160, 16, v160
	v_lshlrev_b32_e32 v161, 16, v161
	v_lshlrev_b32_e32 v162, 16, v162
	v_lshlrev_b32_e32 v163, 16, v163
	v_lshlrev_b32_e32 v164, 16, v164
	s_cmp_ge_i32 s45, 1
	s_cselect_b64 s[56:57], -1, 0
	s_add_i32 s55, s45, 8
	s_cmp_lt_i32 s55, s47
	s_cselect_b64 s[58:59], -1, 0
	v_cndmask_b32_e64 v169, 0, v165, s[56:57]
	v_cndmask_b32_e64 v170, 0, v167, s[58:59]
	v_cndmask_b32_e64 v171, 0, v168, s[58:59]
	v_mul_f32_e32 v172, v166, v155
	v_fmac_f32_e32 v172, v169, v154
	v_fmac_f32_e32 v172, v167, v156
	v_fmac_f32_e32 v172, v168, v157
	v_mul_f32_e32 v173, v166, v156
	v_fmac_f32_e32 v173, v165, v155
	v_fmac_f32_e32 v173, v167, v157
	v_fmac_f32_e32 v173, v168, v158
	v_mul_f32_e32 v174, v166, v157
	v_fmac_f32_e32 v174, v165, v156
	v_fmac_f32_e32 v174, v167, v158
	v_fmac_f32_e32 v174, v168, v159
	v_mul_f32_e32 v175, v166, v158
	v_fmac_f32_e32 v175, v165, v157
	v_fmac_f32_e32 v175, v167, v159
	v_fmac_f32_e32 v175, v168, v160
	v_mul_f32_e32 v176, v166, v159
	v_fmac_f32_e32 v176, v165, v158
	v_fmac_f32_e32 v176, v167, v160
	v_fmac_f32_e32 v176, v168, v161
	v_mul_f32_e32 v177, v166, v160
	v_fmac_f32_e32 v177, v165, v159
	v_fmac_f32_e32 v177, v167, v161
	v_fmac_f32_e32 v177, v168, v162
	v_mul_f32_e32 v178, v166, v161
	v_fmac_f32_e32 v178, v165, v160
	v_fmac_f32_e32 v178, v167, v162
	v_fmac_f32_e32 v178, v171, v163
	v_mul_f32_e32 v179, v166, v162
	v_fmac_f32_e32 v179, v165, v161
	v_fmac_f32_e32 v179, v170, v163
	v_fmac_f32_e32 v179, v171, v164
	v_cvt_pk_bf16_f32 v184, v172, v172
	ds_write_b32 v182, v172
	ds_write_b16 v183, v184 offset:16640
	v_cvt_pk_bf16_f32 v184, v173, v173
	ds_write_b32 v182, v173 offset:260
	ds_write_b16 v183, v184 offset:16784
	v_cvt_pk_bf16_f32 v184, v174, v174
	ds_write_b32 v182, v174 offset:520
	ds_write_b16 v183, v184 offset:16928
	v_cvt_pk_bf16_f32 v184, v175, v175
	ds_write_b32 v182, v175 offset:780
	ds_write_b16 v183, v184 offset:17072
	v_cvt_pk_bf16_f32 v184, v176, v176
	ds_write_b32 v182, v176 offset:1040
	ds_write_b16 v183, v184 offset:17216
	v_cvt_pk_bf16_f32 v184, v177, v177
	ds_write_b32 v182, v177 offset:1300
	ds_write_b16 v183, v184 offset:17360
	v_cvt_pk_bf16_f32 v184, v178, v178
	ds_write_b32 v182, v178 offset:1560
	ds_write_b16 v183, v184 offset:17504
	v_cvt_pk_bf16_f32 v184, v179, v179
	ds_write_b32 v182, v179 offset:1820
	ds_write_b16 v183, v184 offset:17648
	s_waitcnt lgkmcnt(0)
	s_barrier
; __device__ __forceinline__ float fexp(float x) { return __expf(x); }
; __device__ __forceinline__ float sigm(float x) { return frcp(1.f + fexp(-x)); }
; __device__ __forceinline__ float softplusf(float x) { return fmaxf(x, 0.f) + __logf(1.f + fexp(-fabsf(x))); }
; __device__ void rg_tile(unsigned char* lds, const Params& p, int l, int b, int ck, int hh, bool outmode) {
;     ...
;   {
;     const int d = w >> 2, jf = w & 3;
;     f32x4 ar[4], ai[4];
; #pragma unroll
;     for (int i = 0; i < 4; ++i) { ar[i] = (f32x4){0.f, 0.f, 0.f, 0.f}; ai[i] = (f32x4){0.f, 0.f, 0.f, 0.f}; }
; #pragma unroll
;     for (int ks = 0; ks < 2; ++ks) {
;       const bf16x8 wr = ldfrag(WT + ((d * 2 + 0) * 64 + jf * 16 + lr) * 72 + ks * 32 + lg * 8);
;       const bf16x8 wi = ldfrag(WT + ((d * 2 + 1) * 64 + jf * 16 + lr) * 72 + ks * 32 + lg * 8);
; #pragma unroll
;       for (int tf = 0; tf < 4; ++tf) {
;         const bf16x8 xf = ldfrag(XB + (tf * 16 + lr) * 72 + ks * 32 + lg * 8);
;         ar[tf] = mfma16(xf, wr, ar[tf]);
;         ai[tf] = mfma16(xf, wi, ai[tf]);
;       }
;     }
;     const int j = jf * 16 + lr;
;     const int ch = hh * 64 + j;
;     const float sp = softplusf(-lam_);
; #pragma unroll
;     for (int tf = 0; tf < 4; ++tf)
; #pragma unroll
;       for (int jj = 0; jj < 4; ++jj) {
;         const int tt = tf * 16 + lg * 4 + jj;
;         const float r = sigm(ar[tf][jj] + br);
;         const float ig = sigm(ai[tf][jj] + bi);
;         const float la = -8.0f * r * sp;
;         const float a = fexp(la);
;         const float bq = __builtin_amdgcn_sqrtf(fmaxf(1.f - a * a, 0.f)) * ig * XR[tt * 65 + j];
;         AA[(d * 64 + tt) * 64 + j] = a;
;         BQ[(d * 64 + tt) * 64 + j] = bq;
;       }
	ds_read_b128 v[18:21], v17 offset:16640
	v_lshl_or_b32 v1, v56, 7, v55
	v_mad_u64_u32 v[2:3], s[0:1], v1, s11, v[0:1]
	v_lshl_or_b32 v1, v7, 6, v55
	ds_read_b128 v[12:15], v2 offset:25856
	v_mad_u64_u32 v[0:1], s[0:1], v1, s11, v[0:1]
	ds_read_b128 v[4:7], v2 offset:25920
	ds_read_b128 v[22:25], v17 offset:16704
	ds_read_b128 v[8:11], v0 offset:25856
	ds_read_b128 v[0:3], v0 offset:25920
	s_mov_b32 s0, 0xbfb8aa3b
	v_mul_f32_e64 v26, |v16|, s0
	s_waitcnt lgkmcnt(4)
	v_mfma_f32_16x16x32_bf16 v[58:61], v[18:21], v[12:15], 0
	v_exp_f32_e32 v26, v26
	s_mov_b32 s0, 0x800000
	v_max_f32_e64 v16, -v16, -v16
	s_waitcnt lgkmcnt(1)
	v_mfma_f32_16x16x32_bf16 v[18:21], v[18:21], v[8:11], 0
	v_max_f32_e32 v16, 0, v16
	v_bfe_u32 v82, v52, 4, 2
	ds_read_b128 v[62:65], v17 offset:18944
	ds_read_b128 v[66:69], v17 offset:19008
	s_waitcnt lgkmcnt(2)
	v_mfma_f32_16x16x32_bf16 v[74:77], v[22:25], v[0:3], v[18:21]
	v_lshlrev_b32_e32 v56, 12, v56
	v_and_b32_e32 v52, 0x1fffff80, v52
	s_nop 0
	v_add_f32_e32 v18, 1.0, v26
	v_cmp_gt_f32_e32 vcc, s0, v18
	v_mfma_f32_16x16x32_bf16 v[58:61], v[22:25], v[4:7], v[58:61]
	s_mov_b32 s0, 0x3f317217
	v_cndmask_b32_e64 v19, 0, 32, vcc
	v_ldexp_f32 v18, v18, v19
	v_log_f32_e32 v18, v18
	v_mov_b32_e32 v20, 0x41b17218
	v_cndmask_b32_e32 v20, 0, v20, vcc
	s_nop 1
	v_add_f32_e32 v59, v54, v59
	v_mul_f32_e32 v19, 0x3f317217, v18
	v_fma_f32 v19, v18, s0, -v19
	v_fmac_f32_e32 v19, 0x3377d1cf, v18
	s_mov_b32 s0, 0x7f800000
	v_fmac_f32_e32 v19, 0x3f317217, v18
	v_cmp_lt_f32_e64 s[0:1], |v18|, s0
	ds_read_b128 v[78:81], v17 offset:21248
	ds_read_b128 v[24:27], v17 offset:21312
	v_cndmask_b32_e64 v18, v18, v19, s[0:1]
	v_add_f32_e32 v19, v54, v58
	v_mul_f32_e32 v19, 0xbfb8aa3b, v19
	v_exp_f32_e32 v19, v19
	v_sub_f32_e32 v18, v18, v20
	v_add_f32_e32 v57, v16, v18
	v_add_f32_e32 v18, v53, v74
	v_add_f32_e32 v16, 1.0, v19
	v_rcp_f32_e32 v16, v16
	v_mul_f32_e32 v18, 0xbfb8aa3b, v18
	v_exp_f32_e32 v18, v18
	v_lshl_add_u32 v74, v55, 2, 0
	v_mul_f32_e32 v16, 0xc1000000, v16
	v_mul_f32_e32 v16, v57, v16
	v_mul_f32_e32 v16, 0x3fb8aa3b, v16
	v_exp_f32_e32 v58, v16
	v_add_f32_e32 v16, 1.0, v18
	v_rcp_f32_e32 v83, v16
	s_movk_i32 s0, 0x410
	v_fma_f32 v16, -v58, v58, 1.0
	v_max_f32_e32 v16, 0, v16
	v_sqrt_f32_e32 v84, v16
	v_mad_u32_u24 v16, v82, s0, v74
	ds_read_b32 v85, v16
	ds_read_b128 v[20:23], v17 offset:23552
	ds_read_b128 v[16:19], v17 offset:23616
	v_mul_f32_e32 v59, 0xbfb8aa3b, v59
	v_mul_f32_e32 v83, v83, v84
	v_lshlrev_b32_e32 v84, 8, v82
	v_or3_b32 v84, v84, v56, v55
	v_exp_f32_e32 v59, v59
	v_lshlrev_b32_e32 v84, 2, v84
	s_waitcnt lgkmcnt(2)
	v_mul_f32_e32 v83, v85, v83
	v_add_u32_e32 v85, 0, v84
	v_readlane_b32 s0, v253, 37
	ds_write_b32 v85, v58 offset:62720
	v_mfma_f32_16x16x32_bf16 v[70:73], v[62:65], v[12:15], 0
	v_add_u32_e32 v58, s0, v84
	ds_write_b32 v58, v83
	v_add_f32_e32 v58, 1.0, v59
	v_add_f32_e32 v59, v53, v75
	v_lshl_or_b32 v75, v82, 2, 1
	v_rcp_f32_e32 v58, v58
	v_mad_u32_u24 v74, v75, s12, v74
	v_lshlrev_b32_e32 v75, 6, v75
	v_or3_b32 v55, v75, v56, v55
	v_add_f32_e32 v56, v54, v60
	v_mul_f32_e32 v56, 0xbfb8aa3b, v56
	v_exp_f32_e32 v56, v56
	v_mul_f32_e32 v58, 0xc1000000, v58
	v_mul_f32_e32 v58, v57, v58
	v_mul_f32_e32 v58, 0x3fb8aa3b, v58
	v_mul_f32_e32 v59, 0xbfb8aa3b, v59
	v_exp_f32_e32 v58, v58
	v_add_f32_e32 v56, 1.0, v56
	v_exp_f32_e32 v59, v59
	v_rcp_f32_e32 v56, v56
	v_fma_f32 v82, -v58, v58, 1.0
	v_lshlrev_b32_e32 v55, 2, v55
	v_add_f32_e32 v59, 1.0, v59
	v_max_f32_e32 v82, 0, v82
	v_add_u32_e32 v60, 0, v55
	v_mul_f32_e32 v56, 0xc1000000, v56
	v_rcp_f32_e32 v59, v59
	v_sqrt_f32_e32 v82, v82
	ds_read_b32 v83, v74
	ds_write_b32 v60, v58 offset:62720
	v_add_f32_e32 v58, v53, v76
	v_mul_f32_e32 v56, v57, v56
	v_mul_f32_e32 v58, 0xbfb8aa3b, v58
	v_mul_f32_e32 v56, 0x3fb8aa3b, v56
	v_exp_f32_e32 v58, v58
	v_exp_f32_e32 v56, v56
	v_mul_f32_e32 v59, v59, v82
	s_waitcnt lgkmcnt(1)
	v_mul_f32_e32 v59, v83, v59
	v_add_u32_e32 v55, s0, v55
	ds_write_b32 v55, v59
	v_add_f32_e32 v55, 1.0, v58
	v_fma_f32 v58, -v56, v56, 1.0
	v_max_f32_e32 v58, 0, v58
	v_rcp_f32_e32 v55, v55
	v_sqrt_f32_e32 v58, v58
	ds_read_b32 v59, v74 offset:260
	v_mfma_f32_16x16x32_bf16 v[62:65], v[62:65], v[8:11], 0
	v_cmp_eq_u32_e32 vcc, 0, v48
	v_mul_f32_e32 v55, v55, v58
	v_or_b32_e32 v58, 0x200, v84
	s_waitcnt lgkmcnt(0)
	v_mul_f32_e32 v55, v55, v59
	v_add_f32_e32 v59, v54, v61
	v_mul_f32_e32 v59, 0xbfb8aa3b, v59
	v_exp_f32_e32 v59, v59
	v_add_u32_e32 v60, 0, v58
	ds_write_b32 v60, v56 offset:62720
	v_add_u32_e32 v56, s0, v58
	v_add_f32_e32 v58, 1.0, v59
	v_rcp_f32_e32 v58, v58
	v_add_f32_e32 v59, v53, v77
	v_mul_f32_e32 v59, 0xbfb8aa3b, v59
	v_mfma_f32_16x16x32_bf16 v[70:73], v[66:69], v[4:7], v[70:73]
	v_exp_f32_e32 v59, v59
	v_mul_f32_e32 v58, 0xc1000000, v58
	v_mul_f32_e32 v58, v57, v58
	v_mul_f32_e32 v58, 0x3fb8aa3b, v58
	v_exp_f32_e32 v75, v58
	ds_write_b32 v56, v55
	v_add_f32_e32 v55, 1.0, v59
	v_mfma_f32_16x16x32_bf16 v[58:61], v[66:69], v[0:3], v[62:65]
	v_fma_f32 v56, -v75, v75, 1.0
	v_max_f32_e32 v56, 0, v56
	v_rcp_f32_e32 v55, v55
	v_add_f32_e32 v62, v54, v70
	v_mul_f32_e32 v62, 0xbfb8aa3b, v62
	v_exp_f32_e32 v62, v62
	v_sqrt_f32_e32 v56, v56
	ds_read_b32 v76, v74 offset:520
	v_add_f32_e32 v58, v53, v58
	v_add_f32_e32 v62, 1.0, v62
	v_rcp_f32_e32 v62, v62
	v_mul_f32_e32 v58, 0xbfb8aa3b, v58
	v_exp_f32_e32 v58, v58
	v_mul_f32_e32 v55, v55, v56
	v_mul_f32_e32 v62, 0xc1000000, v62
	v_mul_f32_e32 v62, v57, v62
	v_mul_f32_e32 v62, 0x3fb8aa3b, v62
	v_exp_f32_e32 v66, v62
	v_or_b32_e32 v56, 0x300, v84
	s_waitcnt lgkmcnt(0)
; __device__ __forceinline__ float fexp(float x) { return __expf(x); }
; __device__ __forceinline__ float sigm(float x) { return frcp(1.f + fexp(-x)); }
; __device__ void rg_tile(unsigned char* lds, const Params& p, int l, int b, int ck, int hh, bool outmode) {
;     ...
; #pragma unroll
;     for (int tf = 0; tf < 4; ++tf)
; #pragma unroll
;       for (int jj = 0; jj < 4; ++jj) {
;         const int tt = tf * 16 + lg * 4 + jj;
;         const float r = sigm(ar[tf][jj] + br);
;         const float ig = sigm(ai[tf][jj] + bi);
;         const float la = -8.0f * r * sp;
;         const float a = fexp(la);
;         const float bq = __builtin_amdgcn_sqrtf(fmaxf(1.f - a * a, 0.f)) * ig * XR[tt * 65 + j];
;         AA[(d * 64 + tt) * 64 + j] = a;
;         BQ[(d * 64 + tt) * 64 + j] = bq;
;       }
	v_mul_f32_e32 v55, v55, v76
	v_add_u32_e32 v63, 0, v56
	v_add_u32_e32 v56, s0, v56
	ds_write_b32 v56, v55
	v_fma_f32 v56, -v66, v66, 1.0
	ds_write_b32 v63, v75 offset:62720
	v_add_f32_e32 v55, 1.0, v58
	v_max_f32_e32 v56, 0, v56
	v_rcp_f32_e32 v55, v55
	v_sqrt_f32_e32 v56, v56
	ds_read_b32 v58, v74 offset:3900
	v_add_f32_e32 v59, v53, v59
	v_mul_f32_e32 v59, 0xbfb8aa3b, v59
	v_mul_f32_e32 v55, v55, v56
	v_exp_f32_e32 v59, v59
	s_waitcnt lgkmcnt(0)
	v_mul_f32_e32 v55, v55, v58
	v_add_f32_e32 v58, v54, v71
	v_mul_f32_e32 v58, 0xbfb8aa3b, v58
	v_exp_f32_e32 v58, v58
	v_or_b32_e32 v56, 0x1000, v84
	v_add_u32_e32 v67, 0, v56
	v_add_u32_e32 v56, s0, v56
	v_add_f32_e32 v58, 1.0, v58
	v_rcp_f32_e32 v58, v58
	ds_write_b32 v56, v55
	ds_write_b32 v67, v66 offset:62720
	v_add_f32_e32 v55, 1.0, v59
	v_mul_f32_e32 v58, 0xc1000000, v58
	v_mul_f32_e32 v58, v57, v58
	v_mul_f32_e32 v58, 0x3fb8aa3b, v58
	v_exp_f32_e32 v58, v58
	v_rcp_f32_e32 v55, v55
	ds_read_b32 v59, v74 offset:4160
	v_mfma_f32_16x16x32_bf16 v[62:65], v[78:81], v[12:15], 0
	v_fma_f32 v56, -v58, v58, 1.0
	v_max_f32_e32 v56, 0, v56
	v_sqrt_f32_e32 v56, v56
	v_mfma_f32_16x16x32_bf16 v[62:65], v[24:27], v[4:7], v[62:65]
	v_mul_f32_e32 v55, v55, v56
	s_waitcnt lgkmcnt(0)
	v_mul_f32_e32 v55, v55, v59
	v_add_f32_e32 v59, v54, v72
	v_mul_f32_e32 v59, 0xbfb8aa3b, v59
	v_exp_f32_e32 v59, v59
	v_or_b32_e32 v56, 0x1100, v84
	v_add_u32_e32 v70, 0, v56
	ds_write_b32 v70, v58 offset:62720
	v_add_f32_e32 v58, 1.0, v59
	v_rcp_f32_e32 v58, v58
	v_add_f32_e32 v59, v53, v60
	v_mul_f32_e32 v59, 0xbfb8aa3b, v59
	v_exp_f32_e32 v59, v59
	v_mul_f32_e32 v58, 0xc1000000, v58
	v_mul_f32_e32 v58, v57, v58
	v_mul_f32_e32 v58, 0x3fb8aa3b, v58
	v_exp_f32_e32 v58, v58
	v_add_u32_e32 v56, s0, v56
	ds_write_b32 v56, v55
	v_add_f32_e32 v55, 1.0, v59
	v_fma_f32 v56, -v58, v58, 1.0
	v_max_f32_e32 v56, 0, v56
	v_rcp_f32_e32 v55, v55
	v_sqrt_f32_e32 v56, v56
	ds_read_b32 v59, v74 offset:4420
	v_mfma_f32_16x16x32_bf16 v[66:69], v[78:81], v[8:11], 0
	v_mul_f32_e32 v55, v55, v56
	v_or_b32_e32 v56, 0x1200, v84
	s_waitcnt lgkmcnt(0)
	v_mul_f32_e32 v55, v55, v59
	v_add_f32_e32 v59, v54, v73
	v_mul_f32_e32 v59, 0xbfb8aa3b, v59
	v_exp_f32_e32 v59, v59
	v_add_u32_e32 v60, 0, v56
	ds_write_b32 v60, v58 offset:62720
	v_add_u32_e32 v56, s0, v56
	v_add_f32_e32 v58, 1.0, v59
	v_rcp_f32_e32 v58, v58
	v_add_f32_e32 v59, v53, v61
	v_mul_f32_e32 v59, 0xbfb8aa3b, v59
	v_exp_f32_e32 v59, v59
	v_mul_f32_e32 v58, 0xc1000000, v58
	v_mul_f32_e32 v58, v57, v58
	v_mul_f32_e32 v58, 0x3fb8aa3b, v58
	v_exp_f32_e32 v58, v58
	ds_write_b32 v56, v55
	v_add_f32_e32 v55, 1.0, v59
	v_rcp_f32_e32 v55, v55
	v_fma_f32 v56, -v58, v58, 1.0
	v_max_f32_e32 v56, 0, v56
	v_sqrt_f32_e32 v56, v56
	ds_read_b32 v59, v74 offset:4680
	v_mfma_f32_16x16x32_bf16 v[24:27], v[24:27], v[0:3], v[66:69]
	v_mul_f32_e32 v55, v55, v56
	v_or_b32_e32 v56, 0x1300, v84
	s_waitcnt lgkmcnt(0)
	v_mul_f32_e32 v55, v55, v59
	v_add_f32_e32 v59, v54, v62
	v_mul_f32_e32 v59, 0xbfb8aa3b, v59
	v_exp_f32_e32 v59, v59
	v_add_u32_e32 v60, 0, v56
	ds_write_b32 v60, v58 offset:62720
	v_add_f32_e32 v24, v53, v24
	v_add_f32_e32 v58, 1.0, v59
	v_rcp_f32_e32 v58, v58
	v_mul_f32_e32 v24, 0xbfb8aa3b, v24
	v_exp_f32_e32 v24, v24
	v_add_u32_e32 v56, s0, v56
	v_mul_f32_e32 v58, 0xc1000000, v58
	v_mul_f32_e32 v58, v57, v58
	v_mul_f32_e32 v58, 0x3fb8aa3b, v58
	v_exp_f32_e32 v58, v58
	ds_write_b32 v56, v55
	v_add_f32_e32 v24, 1.0, v24
	v_rcp_f32_e32 v24, v24
	v_fma_f32 v55, -v58, v58, 1.0
	v_max_f32_e32 v55, 0, v55
	v_sqrt_f32_e32 v55, v55
	ds_read_b32 v56, v74 offset:8060
	v_mfma_f32_16x16x32_bf16 v[12:15], v[20:23], v[12:15], 0
	v_add_f32_e32 v25, v53, v25
	v_mul_f32_e32 v24, v24, v55
	v_mul_f32_e32 v25, 0xbfb8aa3b, v25
	s_waitcnt lgkmcnt(0)
	v_mul_f32_e32 v24, v24, v56
	v_add_f32_e32 v56, v54, v63
	v_mul_f32_e32 v56, 0xbfb8aa3b, v56
	v_exp_f32_e32 v56, v56
	v_mfma_f32_16x16x32_bf16 v[8:11], v[20:23], v[8:11], 0
	v_add_f32_e32 v22, v54, v64
	v_mul_f32_e32 v22, 0xbfb8aa3b, v22
	v_add_f32_e32 v56, 1.0, v56
	v_rcp_f32_e32 v56, v56
	v_exp_f32_e32 v22, v22
	v_exp_f32_e32 v25, v25
	v_or_b32_e32 v55, 0x2000, v84
	v_mul_f32_e32 v56, 0xc1000000, v56
	v_mul_f32_e32 v56, v57, v56
	v_mul_f32_e32 v56, 0x3fb8aa3b, v56
	v_exp_f32_e32 v56, v56
	v_add_f32_e32 v22, 1.0, v22
	v_rcp_f32_e32 v22, v22
	v_mfma_f32_16x16x32_bf16 v[4:7], v[16:19], v[4:7], v[12:15]
	v_add_u32_e32 v59, 0, v55
	v_add_u32_e32 v55, s0, v55
	ds_write_b32 v55, v24
	v_add_f32_e32 v14, v54, v65
	v_mul_f32_e32 v14, 0xbfb8aa3b, v14
	v_add_f32_e32 v24, 1.0, v25
	v_fma_f32 v25, -v56, v56, 1.0
	v_exp_f32_e32 v14, v14
	ds_write_b32 v59, v58 offset:62720
	v_max_f32_e32 v25, 0, v25
	v_or_b32_e32 v21, 0x2100, v84
	v_mul_f32_e32 v22, 0xc1000000, v22
	v_rcp_f32_e32 v24, v24
	v_sqrt_f32_e32 v25, v25
	ds_read_b32 v55, v74 offset:8320
	v_add_u32_e32 v23, 0, v21
	v_mul_f32_e32 v22, v57, v22
	ds_write_b32 v23, v56 offset:62720
	v_add_f32_e32 v23, v53, v26
	v_mul_f32_e32 v22, 0x3fb8aa3b, v22
	v_mul_f32_e32 v23, 0xbfb8aa3b, v23
	v_exp_f32_e32 v22, v22
	v_add_f32_e32 v14, 1.0, v14
	v_exp_f32_e32 v23, v23
	v_rcp_f32_e32 v14, v14
	v_mul_f32_e32 v20, v24, v25
	v_add_f32_e32 v4, v54, v4
	s_waitcnt lgkmcnt(1)
	v_mul_f32_e32 v20, v20, v55
	v_add_u32_e32 v21, s0, v21
	v_mul_f32_e32 v4, 0xbfb8aa3b, v4
	ds_write_b32 v21, v20
	v_fma_f32 v21, -v22, v22, 1.0
	v_exp_f32_e32 v4, v4
	v_add_f32_e32 v20, 1.0, v23
	v_max_f32_e32 v21, 0, v21
	v_or_b32_e32 v13, 0x2200, v84
	v_mul_f32_e32 v14, 0xc1000000, v14
	v_rcp_f32_e32 v20, v20
	v_sqrt_f32_e32 v21, v21
	ds_read_b32 v23, v74 offset:8580
	v_add_u32_e32 v15, 0, v13
	v_mul_f32_e32 v14, v57, v14
	ds_write_b32 v15, v22 offset:62720
	v_add_f32_e32 v15, v53, v27
	v_mul_f32_e32 v14, 0x3fb8aa3b, v14
	v_mul_f32_e32 v15, 0xbfb8aa3b, v15
	v_exp_f32_e32 v14, v14
	v_add_f32_e32 v4, 1.0, v4
	v_exp_f32_e32 v15, v15
	v_rcp_f32_e32 v4, v4
	v_mul_f32_e32 v12, v20, v21
	s_waitcnt lgkmcnt(1)
; __device__ __forceinline__ float fexp(float x) { return __expf(x); }
; __device__ __forceinline__ float sigm(float x) { return frcp(1.f + fexp(-x)); }
; __device__ void rg_tile(unsigned char* lds, const Params& p, int l, int b, int ck, int hh, bool outmode) {
;     ...
; #pragma unroll
;     for (int tf = 0; tf < 4; ++tf)
; #pragma unroll
;       for (int jj = 0; jj < 4; ++jj) {
;         const int tt = tf * 16 + lg * 4 + jj;
;         const float r = sigm(ar[tf][jj] + br);
;         const float ig = sigm(ai[tf][jj] + bi);
;         const float la = -8.0f * r * sp;
;         const float a = fexp(la);
;         const float bq = __builtin_amdgcn_sqrtf(fmaxf(1.f - a * a, 0.f)) * ig * XR[tt * 65 + j];
;         AA[(d * 64 + tt) * 64 + j] = a;
;         BQ[(d * 64 + tt) * 64 + j] = bq;
;       }
;   }
;   __syncthreads();
;   {
;     float* SEG = XR;
;     const int seg = tid >> 7, d = (tid >> 6) & 1, j = tid & 63;
;     const int ch = hh * 64 + j;
;     const size_t ci = ((size_t)(b * 36 + ck) * 2 + d) * 256 + ch;
;     float H = 0.f, Ap = 1.f;
; #pragma unroll
;     for (int q = 0; q < 16; ++q) {
;       const int pos = seg * 16 + q;
;       const int tt = d == 0 ? pos : 63 - pos;
;       const float a = AA[(d * 64 + tt) * 64 + j];
;       H = a * H + BQ[(d * 64 + tt) * 64 + j];
;       Ap *= a;
;     }
;     SEG[((seg * 2 + d) * 64 + j) * 2 + 0] = Ap;
;     SEG[((seg * 2 + d) * 64 + j) * 2 + 1] = H;
;     __syncthreads();
	v_mul_f32_e32 v12, v12, v23
	v_add_u32_e32 v13, s0, v13
	v_mfma_f32_16x16x32_bf16 v[0:3], v[16:19], v[0:3], v[8:11]
	v_add_f32_e32 v5, v54, v5
	ds_write_b32 v13, v12
	v_fma_f32 v13, -v14, v14, 1.0
	v_mul_f32_e32 v5, 0xbfb8aa3b, v5
	v_add_f32_e32 v12, 1.0, v15
	v_max_f32_e32 v13, 0, v13
	v_mul_f32_e32 v4, 0xc1000000, v4
	v_exp_f32_e32 v5, v5
	v_rcp_f32_e32 v12, v12
	v_sqrt_f32_e32 v13, v13
	ds_read_b32 v15, v74 offset:8840
	v_mul_f32_e32 v4, v57, v4
	v_add_f32_e32 v0, v53, v0
	v_mul_f32_e32 v4, 0x3fb8aa3b, v4
	v_mul_f32_e32 v0, 0xbfb8aa3b, v0
	v_exp_f32_e32 v4, v4
	v_exp_f32_e32 v0, v0
	v_add_f32_e32 v5, 1.0, v5
	v_mul_f32_e32 v8, v12, v13
	v_or_b32_e32 v9, 0x2300, v84
	v_rcp_f32_e32 v5, v5
	s_waitcnt lgkmcnt(0)
	v_mul_f32_e32 v8, v8, v15
	v_add_u32_e32 v10, 0, v9
	v_add_u32_e32 v9, s0, v9
	ds_write_b32 v9, v8
	v_fma_f32 v8, -v4, v4, 1.0
	ds_write_b32 v10, v14 offset:62720
	v_add_f32_e32 v0, 1.0, v0
	v_max_f32_e32 v8, 0, v8
	v_rcp_f32_e32 v0, v0
	v_sqrt_f32_e32 v8, v8
	ds_read_b32 v9, v74 offset:12220
	v_mul_f32_e32 v5, 0xc1000000, v5
	v_add_f32_e32 v1, v53, v1
	v_mul_f32_e32 v5, v57, v5
	v_mul_f32_e32 v1, 0xbfb8aa3b, v1
	v_mul_f32_e32 v5, 0x3fb8aa3b, v5
	v_exp_f32_e32 v1, v1
	v_exp_f32_e32 v5, v5
	v_mul_f32_e32 v0, v0, v8
	v_or_b32_e32 v8, 0x3000, v84
	s_waitcnt lgkmcnt(0)
	v_mul_f32_e32 v0, v0, v9
	v_add_u32_e32 v9, 0, v8
	ds_write_b32 v9, v4 offset:62720
	v_add_u32_e32 v4, s0, v8
	ds_write_b32 v4, v0
	v_add_f32_e32 v0, 1.0, v1
	v_fma_f32 v1, -v5, v5, 1.0
	v_max_f32_e32 v1, 0, v1
	v_rcp_f32_e32 v0, v0
	v_sqrt_f32_e32 v1, v1
	ds_read_b32 v4, v74 offset:12480
	v_add_f32_e32 v2, v53, v2
	v_mul_f32_e32 v2, 0xbfb8aa3b, v2
	v_mul_f32_e32 v0, v0, v1
	v_exp_f32_e32 v2, v2
	s_waitcnt lgkmcnt(0)
	v_mul_f32_e32 v0, v0, v4
	v_add_f32_e32 v4, v54, v6
	v_mul_f32_e32 v4, 0xbfb8aa3b, v4
	v_exp_f32_e32 v4, v4
	v_or_b32_e32 v1, 0x3100, v84
	v_add_u32_e32 v6, 0, v1
	v_add_u32_e32 v1, s0, v1
	v_add_f32_e32 v4, 1.0, v4
	v_rcp_f32_e32 v4, v4
	ds_write_b32 v1, v0
	ds_write_b32 v6, v5 offset:62720
	v_add_f32_e32 v0, 1.0, v2
	v_mul_f32_e32 v4, 0xc1000000, v4
	v_mul_f32_e32 v4, v57, v4
	v_mul_f32_e32 v4, 0x3fb8aa3b, v4
	v_exp_f32_e32 v4, v4
	v_rcp_f32_e32 v0, v0
	ds_read_b32 v2, v74 offset:12740
	v_add_f32_e32 v3, v53, v3
	v_fma_f32 v1, -v4, v4, 1.0
	v_max_f32_e32 v1, 0, v1
	v_sqrt_f32_e32 v1, v1
	v_mul_f32_e32 v3, 0xbfb8aa3b, v3
	v_exp_f32_e32 v3, v3
	v_lshlrev_b32_e32 v20, 4, v33
	v_mul_f32_e32 v0, v0, v1
	s_waitcnt lgkmcnt(0)
	v_mul_f32_e32 v0, v0, v2
	v_add_f32_e32 v2, v54, v7
	v_mul_f32_e32 v2, 0xbfb8aa3b, v2
	v_exp_f32_e32 v2, v2
	v_or_b32_e32 v1, 0x3200, v84
	v_add_u32_e32 v5, 0, v1
	v_add_u32_e32 v1, s0, v1
	v_add_f32_e32 v2, 1.0, v2
	v_rcp_f32_e32 v2, v2
	ds_write_b32 v1, v0
	ds_write_b32 v5, v4 offset:62720
	v_add_f32_e32 v0, 1.0, v3
	v_mul_f32_e32 v2, 0xc1000000, v2
	v_mul_f32_e32 v2, v57, v2
	v_mul_f32_e32 v2, 0x3fb8aa3b, v2
	v_exp_f32_e32 v2, v2
	v_rcp_f32_e32 v0, v0
	ds_read_b32 v3, v74 offset:13000
	v_lshl_or_b32 v57, v48, 12, v29
	v_fma_f32 v1, -v2, v2, 1.0
	v_max_f32_e32 v1, 0, v1
	v_sqrt_f32_e32 v1, v1
	v_or_b32_e32 v8, 11, v20
	v_sub_u32_e32 v9, 63, v8
	v_cndmask_b32_e32 v8, v9, v8, vcc
	v_mul_f32_e32 v0, v0, v1
	v_or_b32_e32 v1, 0x3300, v84
	s_waitcnt lgkmcnt(0)
	v_mul_f32_e32 v0, v0, v3
	v_add_u32_e32 v3, 0, v1
	ds_write_b32 v3, v2 offset:62720
	v_or_b32_e32 v2, 1, v20
	v_sub_u32_e32 v3, 63, v2
	v_cndmask_b32_e32 v2, v3, v2, vcc
	v_lshlrev_b32_e32 v2, 6, v2
	v_add_lshl_u32 v2, v2, v57, 2
	v_add_u32_e32 v16, 0, v2
	v_add_u32_e32 v22, s0, v2
	v_or_b32_e32 v2, 2, v20
	v_sub_u32_e32 v3, 63, v2
	v_cndmask_b32_e32 v2, v3, v2, vcc
	v_lshlrev_b32_e32 v2, 6, v2
	v_add_u32_e32 v1, s0, v1
	v_add_lshl_u32 v2, v2, v57, 2
	ds_write_b32 v1, v0
	v_sub_u32_e32 v0, 63, v20
	v_add_u32_e32 v23, 0, v2
	v_add_u32_e32 v24, s0, v2
	v_or_b32_e32 v2, 3, v20
	v_cndmask_b32_e32 v0, v0, v20, vcc
	v_sub_u32_e32 v3, 63, v2
	v_lshlrev_b32_e32 v0, 6, v0
	v_cndmask_b32_e32 v2, v3, v2, vcc
	v_add_lshl_u32 v1, v0, v57, 2
	v_lshlrev_b32_e32 v2, 6, v2
	v_add_u32_e32 v0, 0, v1
	v_add_lshl_u32 v2, v2, v57, 2
	s_waitcnt lgkmcnt(0)
	s_barrier
	s_and_b32 s0, s44, 1
	s_lshr_b32 s1, s44, 1
	v_and_b32_e32 v190, 63, v195
	v_lshlrev_b32_e32 v189, 3, v195
	s_cmp_eq_u32 s0, 0
	s_cbranch_scc0 .Lrgs_p5_b1
	s_lshl_b32 s2, s1, 12
	s_add_i32 s2, s2, 0xf500
	v_lshl_add_u32 v188, v190, 2, s2
	ds_read_b32 v154, v188 offset:0
	ds_read_b32 v170, v188 offset:32768
	ds_read_b32 v155, v188 offset:256
	ds_read_b32 v171, v188 offset:33024
	ds_read_b32 v156, v188 offset:512
	ds_read_b32 v172, v188 offset:33280
	ds_read_b32 v157, v188 offset:768
	ds_read_b32 v173, v188 offset:33536
	ds_read_b32 v158, v188 offset:1024
	ds_read_b32 v174, v188 offset:33792
	ds_read_b32 v159, v188 offset:1280
	ds_read_b32 v175, v188 offset:34048
	ds_read_b32 v160, v188 offset:1536
	ds_read_b32 v176, v188 offset:34304
	s_waitcnt lgkmcnt(12)
	v_mov_b32_e32 v186, v170
	v_mov_b32_e32 v187, v154
	ds_read_b32 v161, v188 offset:1792
	ds_read_b32 v177, v188 offset:34560
	s_waitcnt lgkmcnt(12)
	v_fma_f32 v186, v155, v186, v171
	v_mul_f32_e32 v187, v187, v155
	ds_read_b32 v162, v188 offset:2048
	ds_read_b32 v178, v188 offset:34816
	s_waitcnt lgkmcnt(12)
	v_fma_f32 v186, v156, v186, v172
	v_mul_f32_e32 v187, v187, v156
	ds_read_b32 v163, v188 offset:2304
	ds_read_b32 v179, v188 offset:35072
	s_waitcnt lgkmcnt(12)
	v_fma_f32 v186, v157, v186, v173
	v_mul_f32_e32 v187, v187, v157
	ds_read_b32 v164, v188 offset:2560
	ds_read_b32 v180, v188 offset:35328
	s_waitcnt lgkmcnt(12)
	v_fma_f32 v186, v158, v186, v174
	v_mul_f32_e32 v187, v187, v158
	ds_read_b32 v165, v188 offset:2816
	ds_read_b32 v181, v188 offset:35584
	s_waitcnt lgkmcnt(12)
	v_fma_f32 v186, v159, v186, v175
	v_mul_f32_e32 v187, v187, v159
	ds_read_b32 v166, v188 offset:3072
	ds_read_b32 v182, v188 offset:35840
	s_waitcnt lgkmcnt(12)
	v_fma_f32 v186, v160, v186, v176
	v_mul_f32_e32 v187, v187, v160
	ds_read_b32 v167, v188 offset:3328
	ds_read_b32 v183, v188 offset:36096
	s_waitcnt lgkmcnt(12)
	v_fma_f32 v186, v161, v186, v177
	v_mul_f32_e32 v187, v187, v161
	ds_read_b32 v168, v188 offset:3584
	ds_read_b32 v184, v188 offset:36352
	s_waitcnt lgkmcnt(12)
	v_fma_f32 v186, v162, v186, v178
	v_mul_f32_e32 v187, v187, v162
	ds_read_b32 v169, v188 offset:3840
	ds_read_b32 v185, v188 offset:36608
	s_waitcnt lgkmcnt(12)
	v_fma_f32 v186, v163, v186, v179
	v_mul_f32_e32 v187, v187, v163
	s_waitcnt lgkmcnt(10)
	v_fma_f32 v186, v164, v186, v180
	v_mul_f32_e32 v187, v187, v164
	s_waitcnt lgkmcnt(8)
	v_fma_f32 v186, v165, v186, v181
	v_mul_f32_e32 v187, v187, v165
	s_waitcnt lgkmcnt(6)
	v_fma_f32 v186, v166, v186, v182
	v_mul_f32_e32 v187, v187, v166
	s_waitcnt lgkmcnt(4)
	v_fma_f32 v186, v167, v186, v183
	v_mul_f32_e32 v187, v187, v167
	s_waitcnt lgkmcnt(2)
	v_fma_f32 v186, v168, v186, v184
	v_mul_f32_e32 v187, v187, v168
	s_waitcnt lgkmcnt(0)
	v_fma_f32 v186, v169, v186, v185
	v_mul_f32_e32 v187, v187, v169
	v_mov_b32_e32 v190, v187
	v_mov_b32_e32 v191, v186
	ds_write_b64 v189, v[190:191]
	s_branch .Lrgs_p5_j1

; __device__ __forceinline__ float bf2f(bf16_t h) { return __uint_as_float(((unsigned)h) << 16); }
; __device__ void rg_tile(unsigned char* lds, const Params& p, int l, int b, int ck, int hh, bool outmode) {
;     ...
;       const int tp = t0 + tt;
;       const int tm1 = tp - 1 >= 0 ? tp - 1 : 0, tp1 = tp + 1 < L ? tp + 1 : L - 1, tp2 = tp + 2 < L ? tp + 2 : L - 1;
;       const float z0 = bf2f(z[(size_t)(rowbase + tm1) * ZS + 2816 + ch]);
;       const float z1 = bf2f(z[(size_t)(rowbase + tp) * ZS + 2816 + ch]);
;       const float z2 = bf2f(z[(size_t)(rowbase + tp1) * ZS + 2816 + ch]);
;       const float z3 = bf2f(z[(size_t)(rowbase + tp2) * ZS + 2816 + ch]);
; __global__ void __launch_bounds__(512) fwd_kernel(Params p) {
;     ...
;       for (int item0 = blockIdx.x; item0 < REP_P5 * (REP_ML * n_ml + REP_RG * n_rg + n_hy); item0 += G_) {
;         int item = (REP_P5 > 1) ? item0 % (n_ml + n_rg + n_hy) : item0;
;         if (REP_ML > 1) item = (item0 < REP_ML * n_ml) ? item0 % n_ml : item0 - (REP_ML - 1) * n_ml;
;         if (REP_RG > 1) item = (item0 < n_ml) ? item0 : ((item0 < n_ml + REP_RG * n_rg) ? n_ml + (item0 - n_ml) % n_rg : item0 - (REP_RG - 1) * n_rg);
;         if (item < n_ml) {
;           const int n = nfirst + item % ncnt, bh = item / ncnt;
;           ml_out_tile(lds, p, l, bh >> 2, bh & 3, n);
;         } else if (item < n_ml + n_rg) {
;           const int tile = item - n_ml;
;           const int hh = tile & 3, ck = cfirst + (tile >> 2) % ccnt, b = tile / (4 * ccnt);
;           rg_tile(lds, p, l, b, ck, hh, true);
.Lrgs_p5_j2:
	s_waitcnt lgkmcnt(0)
	s_barrier
	s_add_i32 s52, s13, s90
	v_readlane_b32 s53, v254, 23
	s_nop 0
	s_mov_b32 s62, 0
	s_cmp_ge_i32 s52, s53
	s_cbranch_scc1 .Lrgpf_skip
	s_mov_b32 s62, 1
	s_sub_i32 s52, s52, s30
	s_and_b32 s54, s52, 3
	s_lshr_b32 s55, s52, 2
	v_readlane_b32 s56, v254, 14
	v_readlane_b32 s57, v254, 11
	s_nop 0
	s_mul_hi_u32 s56, s55, s56
	s_mul_i32 s56, s56, s57
	s_sub_i32 s55, s55, s56
	s_sub_i32 s56, s55, s57
	s_cmp_ge_u32 s55, s57
	s_cselect_b32 s55, s56, s55
	s_sub_i32 s56, s55, s57
	s_cmp_ge_u32 s55, s57
	s_cselect_b32 s55, s56, s55
	v_readlane_b32 s56, v254, 22
	v_readlane_b32 s57, v254, 15
	v_readlane_b32 s59, v254, 16
	s_nop 0
	s_add_i32 s55, s55, s56
	s_mul_hi_u32 s56, s52, s59
	s_mul_i32 s58, s56, s57
	s_sub_i32 s58, s52, s58
	s_add_i32 s59, s56, 1
	s_sub_i32 s60, s58, s57
	s_cmp_ge_u32 s58, s57
	s_cselect_b32 s56, s59, s56
	s_cselect_b32 s58, s60, s58
	s_add_i32 s59, s56, 1
	s_cmp_ge_u32 s58, s57
	s_cselect_b32 s56, s59, s56
	s_lshl_b32 s57, s55, 6
	s_lshl_b32 s58, s56, 8
	s_add_i32 s59, s57, 0xffffff00
	s_add_i32 s58, s58, 0x4000
	s_lshl_b32 s60, s56, 11
	s_movk_i32 s61, 0x7ff
	s_cmp_lt_i32 s55, 4
	s_cselect_b32 s61, 0xff, s61
	s_cselect_b32 s57, s57, s59
	s_cselect_b32 s58, s58, s60
	s_add_i32 s57, s57, -1
	s_lshl_b32 s54, s54, 7
	s_addk_i32 s54, 0x1600
	v_lshrrev_b32_e32 v190, 1, v195
	v_add_u32_e32 v190, s57, v190
	v_max_i32_e32 v190, 0, v190
	v_min_i32_e32 v190, s61, v190
	v_add_u32_e32 v190, s58, v190
	v_mul_u32_u24_e32 v190, 0x1a00, v190
	v_and_b32_e32 v191, 1, v195
	v_lshlrev_b32_e32 v191, 9, v191
	v_add3_u32 v190, v190, v191, s54
	v_cmp_gt_u32_e32 vcc, 0x88, v195
	s_and_saveexec_b64 s[52:53], vcc
	global_load_dword v191, v190, s[88:89]
	s_mov_b64 exec, s[52:53]
; __device__ __forceinline__ bf16_t f2bf(float f) { return (bf16_t)(pack2(f, 0.f) & 0xffffu); }
; __device__ void rg_tile(unsigned char* lds, const Params& p, int l, int b, int ck, int hh, bool outmode) {
;     ...
;   if (outmode) {
;     const int ch = hh * 64 + lane;
;     const float gm = p.in[24][(size_t)l * 1024 + 768 + ch];
; #pragma unroll
;     for (int q = 0; q < 8; ++q) {
;       const int tt = w * 8 + q;
;       const int row = rowbase + t0 + tt;
;       const float hr = AA[tt * 64 + lane] + AA[(64 + tt) * 64 + lane];
;       const float v = hr * gelu_tanh(gp_pre[q]);
;       const float ss = wsum(v * v, lane);
;       const float rn = rsqrtf(ss * (1.f / 64.f) + EPSF);
;       y[(size_t)row * 1024 + 768 + ch] = f2bf(v * rn * gm);
;     }
;     __syncthreads();
;   }
.Lrgpf_skip:
	s_and_b32 s0, s13, 3
	v_bfe_u32 v208, v195, 4, 2
	v_and_b32_e32 v209, 15, v195
	s_lshl_b32 s1, s44, 11
	v_lshlrev_b32_e32 v210, 8, v208
	v_lshl_add_u32 v210, v209, 4, v210
	v_add_u32_e32 v210, s1, v210
	v_add_u32_e32 v210, 0xf500, v210
	ds_read_b128 v[212:215], v210
	ds_read_b128 v[216:219], v210 offset:16384
	ds_read_b128 v[154:157], v210 offset:1024
	ds_read_b128 v[158:161], v210 offset:17408
	v_readlane_b32 s2, v251, 31
	v_readlane_b32 s3, v251, 32
	s_add_i32 s4, s48, s45
	s_lshl_b32 s4, s4, 11
	s_lshl_b32 s5, s0, 7
	s_add_i32 s4, s4, s5
	s_addk_i32 s4, 0x600
	s_add_u32 s2, s2, s4
	s_addc_u32 s3, s3, 0
	v_lshlrev_b32_e32 v211, 11, v208
	v_lshl_add_u32 v211, v209, 3, v211
	v_lshlrev_b32_e32 v162, 16, v204
	v_and_b32_e32 v163, 0xffff0000, v204
	v_lshlrev_b32_e32 v164, 16, v205
	v_and_b32_e32 v165, 0xffff0000, v205
	v_lshlrev_b32_e32 v166, 16, v206
	v_and_b32_e32 v167, 0xffff0000, v206
	v_lshlrev_b32_e32 v168, 16, v207
	v_and_b32_e32 v169, 0xffff0000, v207
	v_mul_f32_e32 v170, 0x3d372713, v162
	v_mul_f32_e32 v171, 0x3d372713, v163
	v_mul_f32_e32 v172, 0x3d372713, v164
	v_mul_f32_e32 v173, 0x3d372713, v165
	v_mul_f32_e32 v174, 0x3d372713, v166
	v_mul_f32_e32 v175, 0x3d372713, v167
	v_mul_f32_e32 v176, 0x3d372713, v168
	v_mul_f32_e32 v177, 0x3d372713, v169
	v_mul_f32_e32 v170, v170, v162
	v_mul_f32_e32 v171, v171, v163
	v_mul_f32_e32 v172, v172, v164
	v_mul_f32_e32 v173, v173, v165
	v_mul_f32_e32 v174, v174, v166
	v_mul_f32_e32 v175, v175, v167
	v_mul_f32_e32 v176, v176, v168
	v_mul_f32_e32 v177, v177, v169
	v_fma_f32 v170, v170, v162, v162
	v_fma_f32 v171, v171, v163, v163
	v_fma_f32 v172, v172, v164, v164
	v_fma_f32 v173, v173, v165, v165
	v_fma_f32 v174, v174, v166, v166
	v_fma_f32 v175, v175, v167, v167
	v_fma_f32 v176, v176, v168, v168
	v_fma_f32 v177, v177, v169, v169
	v_mul_f32_e32 v170, 0x3f4c422a, v170
	v_mul_f32_e32 v171, 0x3f4c422a, v171
	v_mul_f32_e32 v172, 0x3f4c422a, v172
	v_mul_f32_e32 v173, 0x3f4c422a, v173
	v_mul_f32_e32 v174, 0x3f4c422a, v174
	v_mul_f32_e32 v175, 0x3f4c422a, v175
	v_mul_f32_e32 v176, 0x3f4c422a, v176
	v_mul_f32_e32 v177, 0x3f4c422a, v177
	v_add_f32_e32 v170, v170, v170
	v_add_f32_e32 v171, v171, v171
	v_add_f32_e32 v172, v172, v172
	v_add_f32_e32 v173, v173, v173
	v_add_f32_e32 v174, v174, v174
	v_add_f32_e32 v175, v175, v175
	v_add_f32_e32 v176, v176, v176
	v_add_f32_e32 v177, v177, v177
	v_mul_f32_e32 v170, 0x3fb8aa3b, v170
	v_mul_f32_e32 v171, 0x3fb8aa3b, v171
	v_mul_f32_e32 v172, 0x3fb8aa3b, v172
	v_mul_f32_e32 v173, 0x3fb8aa3b, v173
	v_mul_f32_e32 v174, 0x3fb8aa3b, v174
	v_mul_f32_e32 v175, 0x3fb8aa3b, v175
	v_mul_f32_e32 v176, 0x3fb8aa3b, v176
	v_mul_f32_e32 v177, 0x3fb8aa3b, v177
	v_exp_f32_e32 v170, v170
	v_exp_f32_e32 v171, v171
	v_exp_f32_e32 v172, v172
	v_exp_f32_e32 v173, v173
	v_exp_f32_e32 v174, v174
	v_exp_f32_e32 v175, v175
	v_exp_f32_e32 v176, v176
	v_exp_f32_e32 v177, v177
	v_add_f32_e32 v170, 1.0, v170
	v_add_f32_e32 v171, 1.0, v171
	v_add_f32_e32 v172, 1.0, v172
	v_add_f32_e32 v173, 1.0, v173
	v_add_f32_e32 v174, 1.0, v174
	v_add_f32_e32 v175, 1.0, v175
	v_add_f32_e32 v176, 1.0, v176
	v_add_f32_e32 v177, 1.0, v177
	v_rcp_f32_e32 v170, v170
	v_rcp_f32_e32 v171, v171
	v_rcp_f32_e32 v172, v172
	v_rcp_f32_e32 v173, v173
	v_rcp_f32_e32 v174, v174
	v_rcp_f32_e32 v175, v175
	v_rcp_f32_e32 v176, v176
	v_rcp_f32_e32 v177, v177
	v_mul_f32_e32 v162, 0.5, v162
	v_mul_f32_e32 v163, 0.5, v163
	v_mul_f32_e32 v164, 0.5, v164
	v_mul_f32_e32 v165, 0.5, v165
	v_mul_f32_e32 v166, 0.5, v166
	v_mul_f32_e32 v167, 0.5, v167
	v_mul_f32_e32 v168, 0.5, v168
	v_mul_f32_e32 v169, 0.5, v169
	v_fma_f32 v170, v170, -2.0, 1.0
	v_fma_f32 v171, v171, -2.0, 1.0
	v_fma_f32 v172, v172, -2.0, 1.0
	v_fma_f32 v173, v173, -2.0, 1.0
	v_fma_f32 v174, v174, -2.0, 1.0
	v_fma_f32 v175, v175, -2.0, 1.0
	v_fma_f32 v176, v176, -2.0, 1.0
	v_fma_f32 v177, v177, -2.0, 1.0
	v_add_f32_e32 v170, 1.0, v170
	v_add_f32_e32 v171, 1.0, v171
	v_add_f32_e32 v172, 1.0, v172
	v_add_f32_e32 v173, 1.0, v173
	v_add_f32_e32 v174, 1.0, v174
	v_add_f32_e32 v175, 1.0, v175
	v_add_f32_e32 v176, 1.0, v176
	v_add_f32_e32 v177, 1.0, v177
	v_mul_f32_e32 v170, v162, v170
	v_mul_f32_e32 v171, v163, v171
	v_mul_f32_e32 v172, v164, v172
	v_mul_f32_e32 v173, v165, v173
	v_mul_f32_e32 v174, v166, v174
	v_mul_f32_e32 v175, v167, v175
	v_mul_f32_e32 v176, v168, v176
	v_mul_f32_e32 v177, v169, v177
	s_waitcnt lgkmcnt(0)
	v_add_f32_e32 v212, v212, v216
	v_add_f32_e32 v213, v213, v217
	v_add_f32_e32 v214, v214, v218
	v_add_f32_e32 v215, v215, v219
	v_add_f32_e32 v154, v154, v158
	v_add_f32_e32 v155, v155, v159
	v_add_f32_e32 v156, v156, v160
	v_add_f32_e32 v157, v157, v161
	v_mul_f32_e32 v178, v212, v170
	v_mul_f32_e32 v179, v213, v171
	v_mul_f32_e32 v180, v214, v172
	v_mul_f32_e32 v181, v215, v173
	v_mul_f32_e32 v182, v154, v174
	v_mul_f32_e32 v183, v155, v175
	v_mul_f32_e32 v184, v156, v176
	v_mul_f32_e32 v185, v157, v177
	v_mul_f32_e32 v186, v178, v178
	v_mul_f32_e32 v187, v182, v182
	v_fmac_f32_e32 v186, v179, v179
	v_fmac_f32_e32 v187, v183, v183
	v_fmac_f32_e32 v186, v180, v180
	v_fmac_f32_e32 v187, v184, v184
	v_fmac_f32_e32 v186, v181, v181
	v_fmac_f32_e32 v187, v185, v185
	s_nop 1
	v_add_f32_dpp v186, v186, v186 quad_perm:[1,0,3,2] row_mask:0xf bank_mask:0xf
	v_add_f32_dpp v187, v187, v187 quad_perm:[1,0,3,2] row_mask:0xf bank_mask:0xf
	s_nop 0
	v_add_f32_dpp v186, v186, v186 quad_perm:[2,3,0,1] row_mask:0xf bank_mask:0xf
	v_add_f32_dpp v187, v187, v187 quad_perm:[2,3,0,1] row_mask:0xf bank_mask:0xf
	s_nop 0
	v_add_f32_dpp v186, v186, v186 row_half_mirror row_mask:0xf bank_mask:0xf
	v_add_f32_dpp v187, v187, v187 row_half_mirror row_mask:0xf bank_mask:0xf
	s_nop 0
	v_add_f32_dpp v186, v186, v186 row_mirror row_mask:0xf bank_mask:0xf
	v_add_f32_dpp v187, v187, v187 row_mirror row_mask:0xf bank_mask:0xf
	s_nop 0
	v_fmamk_f32 v188, v186, 0x3c800000, v194
	v_fmamk_f32 v189, v187, 0x3c800000, v194
	v_rsq_f32_e32 v188, v188
	v_rsq_f32_e32 v189, v189
	s_nop 0
	v_mul_f32_e32 v178, v178, v188
	v_mul_f32_e32 v179, v179, v188
	v_mul_f32_e32 v180, v180, v188
	v_mul_f32_e32 v181, v181, v188
	v_mul_f32_e32 v182, v182, v189
	v_mul_f32_e32 v183, v183, v189
	v_mul_f32_e32 v184, v184, v189
	v_mul_f32_e32 v185, v185, v189
	v_mul_f32_e32 v178, v178, v200
	v_mul_f32_e32 v179, v179, v201
	v_mul_f32_e32 v180, v180, v202
	v_mul_f32_e32 v181, v181, v203
	v_mul_f32_e32 v182, v182, v200
	v_mul_f32_e32 v183, v183, v201
	v_mul_f32_e32 v184, v184, v202
	v_mul_f32_e32 v185, v185, v203
	v_cvt_pk_bf16_f32 v212, v178, v179
	v_cvt_pk_bf16_f32 v213, v180, v181
	v_cvt_pk_bf16_f32 v154, v182, v183
	v_cvt_pk_bf16_f32 v155, v184, v185
	global_store_dwordx2 v211, v[212:213], s[2:3]
	v_add_u32_e32 v211, 0x2000, v211
	global_store_dwordx2 v211, v[154:155], s[2:3]
	s_cmp_eq_u32 s62, 1
	s_cbranch_scc1 .Lrg_nobar
	s_barrier

; __device__ __forceinline__ int sidx(int dir, int b, int h, int n) { return ((dir * 8 + b) * 4 + h) * 18 + n; }
; __device__ __forceinline__ void ml_prep_load(const float* G, int b, int n, int h, int tid, float* g4) {
;   const bool isctx = n < 2;
;   const int p0 = isctx ? n * 128 : (n - 2) * 128;
;   const float* g = G + (size_t)ml_row_pos(b, isctx, p0 + (tid & 127)) * 16;
;   g4[0] = g[0 + h]; g4[1] = g[4 + h]; g4[2] = g[8 + h]; g4[3] = g[12 + h];
; }
; __device__ void ml_out_tile(unsigned char* lds, const Params& p, int l, int b, int h, int n) {
;     ...
;   float g4[4];
;   ml_prep_load(G, b, n, h, tid, g4);
;   if (tid >= 128 && tid < 384) {
;     const int q = tid - 128, dir = q >> 7, e = q & 127;
;     vec[(14 + dir) * 128 + e] = nst[(size_t)sidx(dir, b, h, n) * 128 + e];
;   }
.LBB0_719:
	v_ashrrev_i32_e32 v1, 31, v0
	v_readlane_b32 s2, v251, 0
	s_and_b32 s21, s12, 3
	v_lshlrev_b64 v[0:1], 6, v[0:1]
	v_readlane_b32 s3, v251, 1
	s_lshl_b32 s96, s21, 2
	s_nop 0
	v_lshl_add_u64 v[0:1], s[2:3], 0, v[0:1]
	v_lshl_add_u64 v[0:1], v[0:1], 0, s[96:97]
	s_movk_i32 s46, 0x80
	v_cmp_gt_u32_e64 s[44:45], s46, v197
	s_and_saveexec_b64 s[46:47], s[44:45]
	global_load_dword v222, v[0:1], off
	global_load_dword v224, v[0:1], off offset:16
	global_load_dword v201, v[0:1], off offset:32
	global_load_dword v220, v[0:1], off offset:48
	s_mov_b64 exec, s[46:47]
	v_add_u32_e32 v0, 0xffffff80, v197
	s_movk_i32 s2, 0x100
	v_cmp_gt_u32_e32 vcc, s2, v0
	s_and_saveexec_b64 s[2:3], vcc
	s_cbranch_execz .LBB0_721
	v_lshrrev_b32_e32 v1, 2, v0
	v_and_b32_e32 v1, 32, v1
	s_and_b32 s6, s12, 0x7ffffffc
	v_add_u32_e32 v1, s6, v1
	v_or_b32_e32 v1, s21, v1
	v_mov_b32_e32 v6, s20
	v_mad_u64_u32 v[6:7], s[6:7], v1, 18, v[6:7]
	v_ashrrev_i32_e32 v7, 31, v6
	v_readlane_b32 s6, v251, 58
	v_lshlrev_b64 v[6:7], 9, v[6:7]
	v_readlane_b32 s7, v251, 59
	v_lshlrev_b32_e32 v192, 2, v2
	v_and_b32_e32 v0, 0x80, v0
	v_lshl_add_u64 v[6:7], s[6:7], 0, v[6:7]
	v_lshl_add_u64 v[6:7], v[6:7], 0, v[192:193]
	global_load_dword v1, v[6:7], off
	v_lshlrev_b32_e32 v0, 2, v0
	v_add3_u32 v0, s94, v0, v192
	s_waitcnt vmcnt(0)
	ds_write_b32 v0, v1 offset:7168
